# select256 pass1/pass2 loops rewritten branch-free (mbcnt compaction, sentinel fill); per-XCD 1us staggered start of up-proj GEMM phase
# speedup vs baseline: 1.0112x; 1.0112x over previous
; __device__ __forceinline__ unsigned f2key(float f) { const unsigned u = __float_as_uint(f); return (u & 0x80000000u) ? ~u : (u | 0x80000000u); }
; #define MK_HADD(p) __hip_atomic_fetch_add((p), 1u, __ATOMIC_RELAXED, __HIP_MEMORY_SCOPE_WORKGROUP)
; #define SEL_LOAD4(v_, i0_) do { _Pragma("unroll") for (int q = 0; q < 16; ++q) { const int i_ = (i0_) + 256 * q + 4 * lane; v_[q] = (i_ < n) ? srow4[i_ >> 2] : (f32x4){0.f, 0.f, 0.f, 0.f}; } } while (0)
; __device__ __forceinline__ void select256(LAS unsigned char* wl, const float* srow, int n, int lane) {
;     ...
;     hist_zero<4096>(hist, lane);
;     for (int i0 = 0; i0 < n; i0 += 4096) {
;         f32x4 v[16]; SEL_LOAD4(v, i0);
; #pragma unroll
;         for (int q = 0; q < 16; ++q)
; #pragma unroll
;             for (int e = 0; e < 4; ++e) { const int i = i0 + 256 * q + 4 * lane + e; if (i < n) MK_HADD(hist + (f2key(v[q][e]) >> 20)); }
;     }
.LBB0_582:
	s_sub_u32 s0, s70, s10
	s_lshr_b32 s1, s0, 8
	v_add_u32_e32 v0, s10, v133
	v_lshlrev_b32_e32 v67, 2, v0
	s_add_u32 s74, s30, 0x1000
	s_addc_u32 s75, s31, 0
	s_add_u32 s76, s30, 0x2000
	s_addc_u32 s77, s31, 0
	s_add_u32 s78, s30, 0x3000
	s_addc_u32 s79, s31, 0
	s_cmp_gt_u32 s1, 0
	s_cbranch_scc1 .Lsel1_full_0
	v_mov_b32_e32 v62, -1
	v_mov_b32_e32 v63, -1
	v_mov_b32_e32 v64, -1
	v_mov_b32_e32 v65, -1
	v_mov_b32_e32 v66, v0
	v_cmp_ge_i32_e32 vcc, s70, v66
	s_mov_b64 exec, vcc
	global_load_dwordx4 v[62:65], v67, s[30:31]
	s_mov_b64 exec, -1
	v_sub_u32_e32 v66, s70, v66
	v_cmp_gt_i32_e64 s[4:5], 1, v66
	v_cmp_gt_i32_e64 s[6:7], 2, v66
	v_cmp_gt_i32_e64 s[8:9], 3, v66
	s_waitcnt vmcnt(0)
	v_cndmask_b32_e64 v63, v63, -1, s[4:5]
	v_cndmask_b32_e64 v64, v64, -1, s[6:7]
	v_cndmask_b32_e64 v65, v65, -1, s[8:9]
	s_branch .Lsel1_proc
.Lsel1_full_0:
	global_load_dwordx4 v[62:65], v67, s[30:31]
	s_cmp_gt_u32 s1, 1
	s_cbranch_scc1 .Lsel1_full_1
	v_mov_b32_e32 v58, -1
	v_mov_b32_e32 v59, -1
	v_mov_b32_e32 v60, -1
	v_mov_b32_e32 v61, -1
	v_add_u32_e32 v66, 0x100, v0
	v_cmp_ge_i32_e32 vcc, s70, v66
	s_mov_b64 exec, vcc
	global_load_dwordx4 v[58:61], v67, s[30:31] offset:1024
	s_mov_b64 exec, -1
	v_sub_u32_e32 v66, s70, v66
	v_cmp_gt_i32_e64 s[4:5], 1, v66
	v_cmp_gt_i32_e64 s[6:7], 2, v66
	v_cmp_gt_i32_e64 s[8:9], 3, v66
	s_waitcnt vmcnt(0)
	v_cndmask_b32_e64 v59, v59, -1, s[4:5]
	v_cndmask_b32_e64 v60, v60, -1, s[6:7]
	v_cndmask_b32_e64 v61, v61, -1, s[8:9]
	s_branch .Lsel1_proc
.Lsel1_full_1:
	global_load_dwordx4 v[58:61], v67, s[30:31] offset:1024
	s_cmp_gt_u32 s1, 2
	s_cbranch_scc1 .Lsel1_full_2
	v_mov_b32_e32 v54, -1
	v_mov_b32_e32 v55, -1
	v_mov_b32_e32 v56, -1
	v_mov_b32_e32 v57, -1
	v_add_u32_e32 v66, 0x200, v0
	v_cmp_ge_i32_e32 vcc, s70, v66
	s_mov_b64 exec, vcc
	global_load_dwordx4 v[54:57], v67, s[30:31] offset:2048
	s_mov_b64 exec, -1
	v_sub_u32_e32 v66, s70, v66
	v_cmp_gt_i32_e64 s[4:5], 1, v66
	v_cmp_gt_i32_e64 s[6:7], 2, v66
	v_cmp_gt_i32_e64 s[8:9], 3, v66
	s_waitcnt vmcnt(0)
	v_cndmask_b32_e64 v55, v55, -1, s[4:5]
	v_cndmask_b32_e64 v56, v56, -1, s[6:7]
	v_cndmask_b32_e64 v57, v57, -1, s[8:9]
	s_branch .Lsel1_proc
.Lsel1_full_2:
	global_load_dwordx4 v[54:57], v67, s[30:31] offset:2048
	s_cmp_gt_u32 s1, 3
	s_cbranch_scc1 .Lsel1_full_3
	v_mov_b32_e32 v50, -1
	v_mov_b32_e32 v51, -1
	v_mov_b32_e32 v52, -1
	v_mov_b32_e32 v53, -1
	v_add_u32_e32 v66, 0x300, v0
	v_cmp_ge_i32_e32 vcc, s70, v66
	s_mov_b64 exec, vcc
	global_load_dwordx4 v[50:53], v67, s[30:31] offset:3072
	s_mov_b64 exec, -1
	v_sub_u32_e32 v66, s70, v66
	v_cmp_gt_i32_e64 s[4:5], 1, v66
	v_cmp_gt_i32_e64 s[6:7], 2, v66
	v_cmp_gt_i32_e64 s[8:9], 3, v66
	s_waitcnt vmcnt(0)
	v_cndmask_b32_e64 v51, v51, -1, s[4:5]
	v_cndmask_b32_e64 v52, v52, -1, s[6:7]
	v_cndmask_b32_e64 v53, v53, -1, s[8:9]
	s_branch .Lsel1_proc
.Lsel1_full_3:
	global_load_dwordx4 v[50:53], v67, s[30:31] offset:3072
	s_cmp_gt_u32 s1, 4
	s_cbranch_scc1 .Lsel1_full_4
	v_mov_b32_e32 v46, -1
	v_mov_b32_e32 v47, -1
	v_mov_b32_e32 v48, -1
	v_mov_b32_e32 v49, -1
	v_add_u32_e32 v66, 0x400, v0
	v_cmp_ge_i32_e32 vcc, s70, v66
	s_mov_b64 exec, vcc
	global_load_dwordx4 v[46:49], v67, s[74:75]
	s_mov_b64 exec, -1
	v_sub_u32_e32 v66, s70, v66
	v_cmp_gt_i32_e64 s[4:5], 1, v66
	v_cmp_gt_i32_e64 s[6:7], 2, v66
	v_cmp_gt_i32_e64 s[8:9], 3, v66
	s_waitcnt vmcnt(0)
	v_cndmask_b32_e64 v47, v47, -1, s[4:5]
	v_cndmask_b32_e64 v48, v48, -1, s[6:7]
	v_cndmask_b32_e64 v49, v49, -1, s[8:9]
	s_branch .Lsel1_proc
.Lsel1_full_4:
	global_load_dwordx4 v[46:49], v67, s[74:75]
	s_cmp_gt_u32 s1, 5
	s_cbranch_scc1 .Lsel1_full_5
	v_mov_b32_e32 v42, -1
	v_mov_b32_e32 v43, -1
	v_mov_b32_e32 v44, -1
	v_mov_b32_e32 v45, -1
	v_add_u32_e32 v66, 0x500, v0
	v_cmp_ge_i32_e32 vcc, s70, v66
	s_mov_b64 exec, vcc
	global_load_dwordx4 v[42:45], v67, s[74:75] offset:1024
	s_mov_b64 exec, -1
	v_sub_u32_e32 v66, s70, v66
	v_cmp_gt_i32_e64 s[4:5], 1, v66
	v_cmp_gt_i32_e64 s[6:7], 2, v66
	v_cmp_gt_i32_e64 s[8:9], 3, v66
	s_waitcnt vmcnt(0)
	v_cndmask_b32_e64 v43, v43, -1, s[4:5]
	v_cndmask_b32_e64 v44, v44, -1, s[6:7]
	v_cndmask_b32_e64 v45, v45, -1, s[8:9]
	s_branch .Lsel1_proc
.Lsel1_full_5:
	global_load_dwordx4 v[42:45], v67, s[74:75] offset:1024
	s_cmp_gt_u32 s1, 6
	s_cbranch_scc1 .Lsel1_full_6
	v_mov_b32_e32 v38, -1
	v_mov_b32_e32 v39, -1
	v_mov_b32_e32 v40, -1
	v_mov_b32_e32 v41, -1
	v_add_u32_e32 v66, 0x600, v0
	v_cmp_ge_i32_e32 vcc, s70, v66
	s_mov_b64 exec, vcc
	global_load_dwordx4 v[38:41], v67, s[74:75] offset:2048
	s_mov_b64 exec, -1
	v_sub_u32_e32 v66, s70, v66
	v_cmp_gt_i32_e64 s[4:5], 1, v66
	v_cmp_gt_i32_e64 s[6:7], 2, v66
	v_cmp_gt_i32_e64 s[8:9], 3, v66
	s_waitcnt vmcnt(0)
	v_cndmask_b32_e64 v39, v39, -1, s[4:5]
	v_cndmask_b32_e64 v40, v40, -1, s[6:7]
	v_cndmask_b32_e64 v41, v41, -1, s[8:9]
	s_branch .Lsel1_proc
.Lsel1_full_6:
	global_load_dwordx4 v[38:41], v67, s[74:75] offset:2048
	s_cmp_gt_u32 s1, 7
	s_cbranch_scc1 .Lsel1_full_7
	v_mov_b32_e32 v34, -1
	v_mov_b32_e32 v35, -1
	v_mov_b32_e32 v36, -1
	v_mov_b32_e32 v37, -1
	v_add_u32_e32 v66, 0x700, v0
	v_cmp_ge_i32_e32 vcc, s70, v66
	s_mov_b64 exec, vcc
	global_load_dwordx4 v[34:37], v67, s[74:75] offset:3072
	s_mov_b64 exec, -1
	v_sub_u32_e32 v66, s70, v66
	v_cmp_gt_i32_e64 s[4:5], 1, v66
	v_cmp_gt_i32_e64 s[6:7], 2, v66
	v_cmp_gt_i32_e64 s[8:9], 3, v66
	s_waitcnt vmcnt(0)
	v_cndmask_b32_e64 v35, v35, -1, s[4:5]
	v_cndmask_b32_e64 v36, v36, -1, s[6:7]
	v_cndmask_b32_e64 v37, v37, -1, s[8:9]
	s_branch .Lsel1_proc
; __device__ __forceinline__ unsigned f2key(float f) { const unsigned u = __float_as_uint(f); return (u & 0x80000000u) ? ~u : (u | 0x80000000u); }
; #define MK_HADD(p) __hip_atomic_fetch_add((p), 1u, __ATOMIC_RELAXED, __HIP_MEMORY_SCOPE_WORKGROUP)
; #define SEL_LOAD4(v_, i0_) do { _Pragma("unroll") for (int q = 0; q < 16; ++q) { const int i_ = (i0_) + 256 * q + 4 * lane; v_[q] = (i_ < n) ? srow4[i_ >> 2] : (f32x4){0.f, 0.f, 0.f, 0.f}; } } while (0)
; __device__ __forceinline__ void select256(LAS unsigned char* wl, const float* srow, int n, int lane) {
;     ...
;     hist_zero<4096>(hist, lane);
;     for (int i0 = 0; i0 < n; i0 += 4096) {
;         f32x4 v[16]; SEL_LOAD4(v, i0);
; #pragma unroll
;         for (int q = 0; q < 16; ++q)
; #pragma unroll
;             for (int e = 0; e < 4; ++e) { const int i = i0 + 256 * q + 4 * lane + e; if (i < n) MK_HADD(hist + (f2key(v[q][e]) >> 20)); }
;     }
.Lsel1_full_7:
	global_load_dwordx4 v[34:37], v67, s[74:75] offset:3072
	s_cmp_gt_u32 s1, 8
	s_cbranch_scc1 .Lsel1_full_8
	v_mov_b32_e32 v30, -1
	v_mov_b32_e32 v31, -1
	v_mov_b32_e32 v32, -1
	v_mov_b32_e32 v33, -1
	v_add_u32_e32 v66, 0x800, v0
	v_cmp_ge_i32_e32 vcc, s70, v66
	s_mov_b64 exec, vcc
	global_load_dwordx4 v[30:33], v67, s[76:77]
	s_mov_b64 exec, -1
	v_sub_u32_e32 v66, s70, v66
	v_cmp_gt_i32_e64 s[4:5], 1, v66
	v_cmp_gt_i32_e64 s[6:7], 2, v66
	v_cmp_gt_i32_e64 s[8:9], 3, v66
	s_waitcnt vmcnt(0)
	v_cndmask_b32_e64 v31, v31, -1, s[4:5]
	v_cndmask_b32_e64 v32, v32, -1, s[6:7]
	v_cndmask_b32_e64 v33, v33, -1, s[8:9]
	s_branch .Lsel1_proc
.Lsel1_full_8:
	global_load_dwordx4 v[30:33], v67, s[76:77]
	s_cmp_gt_u32 s1, 9
	s_cbranch_scc1 .Lsel1_full_9
	v_mov_b32_e32 v26, -1
	v_mov_b32_e32 v27, -1
	v_mov_b32_e32 v28, -1
	v_mov_b32_e32 v29, -1
	v_add_u32_e32 v66, 0x900, v0
	v_cmp_ge_i32_e32 vcc, s70, v66
	s_mov_b64 exec, vcc
	global_load_dwordx4 v[26:29], v67, s[76:77] offset:1024
	s_mov_b64 exec, -1
	v_sub_u32_e32 v66, s70, v66
	v_cmp_gt_i32_e64 s[4:5], 1, v66
	v_cmp_gt_i32_e64 s[6:7], 2, v66
	v_cmp_gt_i32_e64 s[8:9], 3, v66
	s_waitcnt vmcnt(0)
	v_cndmask_b32_e64 v27, v27, -1, s[4:5]
	v_cndmask_b32_e64 v28, v28, -1, s[6:7]
	v_cndmask_b32_e64 v29, v29, -1, s[8:9]
	s_branch .Lsel1_proc
.Lsel1_full_9:
	global_load_dwordx4 v[26:29], v67, s[76:77] offset:1024
	s_cmp_gt_u32 s1, 10
	s_cbranch_scc1 .Lsel1_full_10
	v_mov_b32_e32 v22, -1
	v_mov_b32_e32 v23, -1
	v_mov_b32_e32 v24, -1
	v_mov_b32_e32 v25, -1
	v_add_u32_e32 v66, 0xa00, v0
	v_cmp_ge_i32_e32 vcc, s70, v66
	s_mov_b64 exec, vcc
	global_load_dwordx4 v[22:25], v67, s[76:77] offset:2048
	s_mov_b64 exec, -1
	v_sub_u32_e32 v66, s70, v66
	v_cmp_gt_i32_e64 s[4:5], 1, v66
	v_cmp_gt_i32_e64 s[6:7], 2, v66
	v_cmp_gt_i32_e64 s[8:9], 3, v66
	s_waitcnt vmcnt(0)
	v_cndmask_b32_e64 v23, v23, -1, s[4:5]
	v_cndmask_b32_e64 v24, v24, -1, s[6:7]
	v_cndmask_b32_e64 v25, v25, -1, s[8:9]
	s_branch .Lsel1_proc
.Lsel1_full_10:
	global_load_dwordx4 v[22:25], v67, s[76:77] offset:2048
	s_cmp_gt_u32 s1, 11
	s_cbranch_scc1 .Lsel1_full_11
	v_mov_b32_e32 v18, -1
	v_mov_b32_e32 v19, -1
	v_mov_b32_e32 v20, -1
	v_mov_b32_e32 v21, -1
	v_add_u32_e32 v66, 0xb00, v0
	v_cmp_ge_i32_e32 vcc, s70, v66
	s_mov_b64 exec, vcc
	global_load_dwordx4 v[18:21], v67, s[76:77] offset:3072
	s_mov_b64 exec, -1
	v_sub_u32_e32 v66, s70, v66
	v_cmp_gt_i32_e64 s[4:5], 1, v66
	v_cmp_gt_i32_e64 s[6:7], 2, v66
	v_cmp_gt_i32_e64 s[8:9], 3, v66
	s_waitcnt vmcnt(0)
	v_cndmask_b32_e64 v19, v19, -1, s[4:5]
	v_cndmask_b32_e64 v20, v20, -1, s[6:7]
	v_cndmask_b32_e64 v21, v21, -1, s[8:9]
	s_branch .Lsel1_proc
.Lsel1_full_11:
	global_load_dwordx4 v[18:21], v67, s[76:77] offset:3072
	s_cmp_gt_u32 s1, 12
	s_cbranch_scc1 .Lsel1_full_12
	v_mov_b32_e32 v14, -1
	v_mov_b32_e32 v15, -1
	v_mov_b32_e32 v16, -1
	v_mov_b32_e32 v17, -1
	v_add_u32_e32 v66, 0xc00, v0
	v_cmp_ge_i32_e32 vcc, s70, v66
	s_mov_b64 exec, vcc
	global_load_dwordx4 v[14:17], v67, s[78:79]
	s_mov_b64 exec, -1
	v_sub_u32_e32 v66, s70, v66
	v_cmp_gt_i32_e64 s[4:5], 1, v66
	v_cmp_gt_i32_e64 s[6:7], 2, v66
	v_cmp_gt_i32_e64 s[8:9], 3, v66
	s_waitcnt vmcnt(0)
	v_cndmask_b32_e64 v15, v15, -1, s[4:5]
	v_cndmask_b32_e64 v16, v16, -1, s[6:7]
	v_cndmask_b32_e64 v17, v17, -1, s[8:9]
	s_branch .Lsel1_proc
.Lsel1_full_12:
	global_load_dwordx4 v[14:17], v67, s[78:79]
	s_cmp_gt_u32 s1, 13
	s_cbranch_scc1 .Lsel1_full_13
	v_mov_b32_e32 v10, -1
	v_mov_b32_e32 v11, -1
	v_mov_b32_e32 v12, -1
	v_mov_b32_e32 v13, -1
	v_add_u32_e32 v66, 0xd00, v0
	v_cmp_ge_i32_e32 vcc, s70, v66
	s_mov_b64 exec, vcc
	global_load_dwordx4 v[10:13], v67, s[78:79] offset:1024
	s_mov_b64 exec, -1
	v_sub_u32_e32 v66, s70, v66
	v_cmp_gt_i32_e64 s[4:5], 1, v66
	v_cmp_gt_i32_e64 s[6:7], 2, v66
	v_cmp_gt_i32_e64 s[8:9], 3, v66
	s_waitcnt vmcnt(0)
	v_cndmask_b32_e64 v11, v11, -1, s[4:5]
	v_cndmask_b32_e64 v12, v12, -1, s[6:7]
	v_cndmask_b32_e64 v13, v13, -1, s[8:9]
	s_branch .Lsel1_proc
.Lsel1_full_13:
	global_load_dwordx4 v[10:13], v67, s[78:79] offset:1024
	s_cmp_gt_u32 s1, 14
	s_cbranch_scc1 .Lsel1_full_14
	v_mov_b32_e32 v6, -1
	v_mov_b32_e32 v7, -1
	v_mov_b32_e32 v8, -1
	v_mov_b32_e32 v9, -1
	v_add_u32_e32 v66, 0xe00, v0
	v_cmp_ge_i32_e32 vcc, s70, v66
	s_mov_b64 exec, vcc
	global_load_dwordx4 v[6:9], v67, s[78:79] offset:2048
	s_mov_b64 exec, -1
	v_sub_u32_e32 v66, s70, v66
	v_cmp_gt_i32_e64 s[4:5], 1, v66
	v_cmp_gt_i32_e64 s[6:7], 2, v66
	v_cmp_gt_i32_e64 s[8:9], 3, v66
	s_waitcnt vmcnt(0)
	v_cndmask_b32_e64 v7, v7, -1, s[4:5]
	v_cndmask_b32_e64 v8, v8, -1, s[6:7]
	v_cndmask_b32_e64 v9, v9, -1, s[8:9]
	s_branch .Lsel1_proc
.Lsel1_full_14:
	global_load_dwordx4 v[6:9], v67, s[78:79] offset:2048
	s_cmp_gt_u32 s1, 15
	s_cbranch_scc1 .Lsel1_full_15
	v_mov_b32_e32 v2, -1
	v_mov_b32_e32 v3, -1
	v_mov_b32_e32 v4, -1
	v_mov_b32_e32 v5, -1
	v_add_u32_e32 v66, 0xf00, v0
	v_cmp_ge_i32_e32 vcc, s70, v66
	s_mov_b64 exec, vcc
	global_load_dwordx4 v[2:5], v67, s[78:79] offset:3072
	s_mov_b64 exec, -1
	v_sub_u32_e32 v66, s70, v66
	v_cmp_gt_i32_e64 s[4:5], 1, v66
	v_cmp_gt_i32_e64 s[6:7], 2, v66
	v_cmp_gt_i32_e64 s[8:9], 3, v66
	s_waitcnt vmcnt(0)
	v_cndmask_b32_e64 v3, v3, -1, s[4:5]
	v_cndmask_b32_e64 v4, v4, -1, s[6:7]
	v_cndmask_b32_e64 v5, v5, -1, s[8:9]
	s_branch .Lsel1_proc
.Lsel1_full_15:
	global_load_dwordx4 v[2:5], v67, s[78:79] offset:3072
	s_waitcnt vmcnt(0)
; #define MK_HADD(p) __hip_atomic_fetch_add((p), 1u, __ATOMIC_RELAXED, __HIP_MEMORY_SCOPE_WORKGROUP)
; #define SEL_LOAD4(v_, i0_) do { _Pragma("unroll") for (int q = 0; q < 16; ++q) { const int i_ = (i0_) + 256 * q + 4 * lane; v_[q] = (i_ < n) ? srow4[i_ >> 2] : (f32x4){0.f, 0.f, 0.f, 0.f}; } } while (0)
; __device__ __forceinline__ unsigned f2key(float f) { const unsigned u = __float_as_uint(f); return (u & 0x80000000u) ? ~u : (u | 0x80000000u); }
; __device__ __forceinline__ void select256(LAS unsigned char* wl, const float* srow, int n, int lane) {
;     ...
;     for (int i0 = 0; i0 < n; i0 += 4096) {
;         f32x4 v[16]; SEL_LOAD4(v, i0);
; #pragma unroll
;         for (int q = 0; q < 16; ++q)
; #pragma unroll
;             for (int e = 0; e < 4; ++e) { const int i = i0 + 256 * q + 4 * lane + e; if (i < n) MK_HADD(hist + (f2key(v[q][e]) >> 20)); }
;     }
.Lsel1_proc:
	v_ashrrev_i32_e32 v66, 31, v62
	v_or_b32_e32 v66, 0x80000000, v66
	v_xor_b32_e32 v62, v62, v66
	v_bfe_u32 v62, v62, 20, 12
	v_lshl_add_u32 v62, v62, 2, s33
	ds_add_u32 v62, v225
	v_ashrrev_i32_e32 v67, 31, v63
	v_or_b32_e32 v67, 0x80000000, v67
	v_xor_b32_e32 v63, v63, v67
	v_bfe_u32 v63, v63, 20, 12
	v_lshl_add_u32 v63, v63, 2, s33
	ds_add_u32 v63, v225
	v_ashrrev_i32_e32 v66, 31, v64
	v_or_b32_e32 v66, 0x80000000, v66
	v_xor_b32_e32 v64, v64, v66
	v_bfe_u32 v64, v64, 20, 12
	v_lshl_add_u32 v64, v64, 2, s33
	ds_add_u32 v64, v225
	v_ashrrev_i32_e32 v67, 31, v65
	v_or_b32_e32 v67, 0x80000000, v67
	v_xor_b32_e32 v65, v65, v67
	v_bfe_u32 v65, v65, 20, 12
	v_lshl_add_u32 v65, v65, 2, s33
	ds_add_u32 v65, v225
	s_cmp_eq_u32 s1, 0
	s_cbranch_scc1 .Lsel1_done
	v_ashrrev_i32_e32 v66, 31, v58
	v_or_b32_e32 v66, 0x80000000, v66
	v_xor_b32_e32 v58, v58, v66
	v_bfe_u32 v58, v58, 20, 12
	v_lshl_add_u32 v58, v58, 2, s33
	ds_add_u32 v58, v225
	v_ashrrev_i32_e32 v67, 31, v59
	v_or_b32_e32 v67, 0x80000000, v67
	v_xor_b32_e32 v59, v59, v67
	v_bfe_u32 v59, v59, 20, 12
	v_lshl_add_u32 v59, v59, 2, s33
	ds_add_u32 v59, v225
	v_ashrrev_i32_e32 v66, 31, v60
	v_or_b32_e32 v66, 0x80000000, v66
	v_xor_b32_e32 v60, v60, v66
	v_bfe_u32 v60, v60, 20, 12
	v_lshl_add_u32 v60, v60, 2, s33
	ds_add_u32 v60, v225
	v_ashrrev_i32_e32 v67, 31, v61
	v_or_b32_e32 v67, 0x80000000, v67
	v_xor_b32_e32 v61, v61, v67
	v_bfe_u32 v61, v61, 20, 12
	v_lshl_add_u32 v61, v61, 2, s33
	ds_add_u32 v61, v225
	s_cmp_eq_u32 s1, 1
	s_cbranch_scc1 .Lsel1_done
	v_ashrrev_i32_e32 v66, 31, v54
	v_or_b32_e32 v66, 0x80000000, v66
	v_xor_b32_e32 v54, v54, v66
	v_bfe_u32 v54, v54, 20, 12
	v_lshl_add_u32 v54, v54, 2, s33
	ds_add_u32 v54, v225
	v_ashrrev_i32_e32 v67, 31, v55
	v_or_b32_e32 v67, 0x80000000, v67
	v_xor_b32_e32 v55, v55, v67
	v_bfe_u32 v55, v55, 20, 12
	v_lshl_add_u32 v55, v55, 2, s33
	ds_add_u32 v55, v225
	v_ashrrev_i32_e32 v66, 31, v56
	v_or_b32_e32 v66, 0x80000000, v66
	v_xor_b32_e32 v56, v56, v66
	v_bfe_u32 v56, v56, 20, 12
	v_lshl_add_u32 v56, v56, 2, s33
	ds_add_u32 v56, v225
	v_ashrrev_i32_e32 v67, 31, v57
	v_or_b32_e32 v67, 0x80000000, v67
	v_xor_b32_e32 v57, v57, v67
	v_bfe_u32 v57, v57, 20, 12
	v_lshl_add_u32 v57, v57, 2, s33
	ds_add_u32 v57, v225
	s_cmp_eq_u32 s1, 2
	s_cbranch_scc1 .Lsel1_done
	v_ashrrev_i32_e32 v66, 31, v50
	v_or_b32_e32 v66, 0x80000000, v66
	v_xor_b32_e32 v50, v50, v66
	v_bfe_u32 v50, v50, 20, 12
	v_lshl_add_u32 v50, v50, 2, s33
	ds_add_u32 v50, v225
	v_ashrrev_i32_e32 v67, 31, v51
	v_or_b32_e32 v67, 0x80000000, v67
	v_xor_b32_e32 v51, v51, v67
	v_bfe_u32 v51, v51, 20, 12
	v_lshl_add_u32 v51, v51, 2, s33
	ds_add_u32 v51, v225
	v_ashrrev_i32_e32 v66, 31, v52
	v_or_b32_e32 v66, 0x80000000, v66
	v_xor_b32_e32 v52, v52, v66
	v_bfe_u32 v52, v52, 20, 12
	v_lshl_add_u32 v52, v52, 2, s33
	ds_add_u32 v52, v225
	v_ashrrev_i32_e32 v67, 31, v53
	v_or_b32_e32 v67, 0x80000000, v67
	v_xor_b32_e32 v53, v53, v67
	v_bfe_u32 v53, v53, 20, 12
	v_lshl_add_u32 v53, v53, 2, s33
	ds_add_u32 v53, v225
	s_cmp_eq_u32 s1, 3
	s_cbranch_scc1 .Lsel1_done
	v_ashrrev_i32_e32 v66, 31, v46
	v_or_b32_e32 v66, 0x80000000, v66
	v_xor_b32_e32 v46, v46, v66
	v_bfe_u32 v46, v46, 20, 12
	v_lshl_add_u32 v46, v46, 2, s33
	ds_add_u32 v46, v225
	v_ashrrev_i32_e32 v67, 31, v47
	v_or_b32_e32 v67, 0x80000000, v67
	v_xor_b32_e32 v47, v47, v67
	v_bfe_u32 v47, v47, 20, 12
	v_lshl_add_u32 v47, v47, 2, s33
	ds_add_u32 v47, v225
	v_ashrrev_i32_e32 v66, 31, v48
	v_or_b32_e32 v66, 0x80000000, v66
	v_xor_b32_e32 v48, v48, v66
	v_bfe_u32 v48, v48, 20, 12
	v_lshl_add_u32 v48, v48, 2, s33
	ds_add_u32 v48, v225
	v_ashrrev_i32_e32 v67, 31, v49
	v_or_b32_e32 v67, 0x80000000, v67
	v_xor_b32_e32 v49, v49, v67
	v_bfe_u32 v49, v49, 20, 12
	v_lshl_add_u32 v49, v49, 2, s33
	ds_add_u32 v49, v225
	s_cmp_eq_u32 s1, 4
	s_cbranch_scc1 .Lsel1_done
	v_ashrrev_i32_e32 v66, 31, v42
	v_or_b32_e32 v66, 0x80000000, v66
	v_xor_b32_e32 v42, v42, v66
	v_bfe_u32 v42, v42, 20, 12
	v_lshl_add_u32 v42, v42, 2, s33
	ds_add_u32 v42, v225
	v_ashrrev_i32_e32 v67, 31, v43
	v_or_b32_e32 v67, 0x80000000, v67
	v_xor_b32_e32 v43, v43, v67
	v_bfe_u32 v43, v43, 20, 12
	v_lshl_add_u32 v43, v43, 2, s33
	ds_add_u32 v43, v225
	v_ashrrev_i32_e32 v66, 31, v44
	v_or_b32_e32 v66, 0x80000000, v66
	v_xor_b32_e32 v44, v44, v66
	v_bfe_u32 v44, v44, 20, 12
	v_lshl_add_u32 v44, v44, 2, s33
	ds_add_u32 v44, v225
	v_ashrrev_i32_e32 v67, 31, v45
	v_or_b32_e32 v67, 0x80000000, v67
	v_xor_b32_e32 v45, v45, v67
	v_bfe_u32 v45, v45, 20, 12
	v_lshl_add_u32 v45, v45, 2, s33
	ds_add_u32 v45, v225
	s_cmp_eq_u32 s1, 5
	s_cbranch_scc1 .Lsel1_done
	v_ashrrev_i32_e32 v66, 31, v38
	v_or_b32_e32 v66, 0x80000000, v66
	v_xor_b32_e32 v38, v38, v66
	v_bfe_u32 v38, v38, 20, 12
	v_lshl_add_u32 v38, v38, 2, s33
	ds_add_u32 v38, v225
	v_ashrrev_i32_e32 v67, 31, v39
	v_or_b32_e32 v67, 0x80000000, v67
	v_xor_b32_e32 v39, v39, v67
	v_bfe_u32 v39, v39, 20, 12
	v_lshl_add_u32 v39, v39, 2, s33
	ds_add_u32 v39, v225
	v_ashrrev_i32_e32 v66, 31, v40
	v_or_b32_e32 v66, 0x80000000, v66
	v_xor_b32_e32 v40, v40, v66
	v_bfe_u32 v40, v40, 20, 12
	v_lshl_add_u32 v40, v40, 2, s33
	ds_add_u32 v40, v225
	v_ashrrev_i32_e32 v67, 31, v41
	v_or_b32_e32 v67, 0x80000000, v67
	v_xor_b32_e32 v41, v41, v67
	v_bfe_u32 v41, v41, 20, 12
	v_lshl_add_u32 v41, v41, 2, s33
	ds_add_u32 v41, v225
	s_cmp_eq_u32 s1, 6
	s_cbranch_scc1 .Lsel1_done
; __device__ __forceinline__ unsigned f2key(float f) { const unsigned u = __float_as_uint(f); return (u & 0x80000000u) ? ~u : (u | 0x80000000u); }
; #define MK_HADD(p) __hip_atomic_fetch_add((p), 1u, __ATOMIC_RELAXED, __HIP_MEMORY_SCOPE_WORKGROUP)
; #define SEL_LOAD4(v_, i0_) do { _Pragma("unroll") for (int q = 0; q < 16; ++q) { const int i_ = (i0_) + 256 * q + 4 * lane; v_[q] = (i_ < n) ? srow4[i_ >> 2] : (f32x4){0.f, 0.f, 0.f, 0.f}; } } while (0)
; __device__ __forceinline__ void select256(LAS unsigned char* wl, const float* srow, int n, int lane) {
;     ...
;     for (int i0 = 0; i0 < n; i0 += 4096) {
;         f32x4 v[16]; SEL_LOAD4(v, i0);
; #pragma unroll
;         for (int q = 0; q < 16; ++q)
; #pragma unroll
;             for (int e = 0; e < 4; ++e) { const int i = i0 + 256 * q + 4 * lane + e; if (i < n) MK_HADD(hist + (f2key(v[q][e]) >> 20)); }
;     }
;     const unsigned b1 = find_bin<12>(hist, k, lane);
	v_ashrrev_i32_e32 v66, 31, v34
	v_or_b32_e32 v66, 0x80000000, v66
	v_xor_b32_e32 v34, v34, v66
	v_bfe_u32 v34, v34, 20, 12
	v_lshl_add_u32 v34, v34, 2, s33
	ds_add_u32 v34, v225
	v_ashrrev_i32_e32 v67, 31, v35
	v_or_b32_e32 v67, 0x80000000, v67
	v_xor_b32_e32 v35, v35, v67
	v_bfe_u32 v35, v35, 20, 12
	v_lshl_add_u32 v35, v35, 2, s33
	ds_add_u32 v35, v225
	v_ashrrev_i32_e32 v66, 31, v36
	v_or_b32_e32 v66, 0x80000000, v66
	v_xor_b32_e32 v36, v36, v66
	v_bfe_u32 v36, v36, 20, 12
	v_lshl_add_u32 v36, v36, 2, s33
	ds_add_u32 v36, v225
	v_ashrrev_i32_e32 v67, 31, v37
	v_or_b32_e32 v67, 0x80000000, v67
	v_xor_b32_e32 v37, v37, v67
	v_bfe_u32 v37, v37, 20, 12
	v_lshl_add_u32 v37, v37, 2, s33
	ds_add_u32 v37, v225
	s_cmp_eq_u32 s1, 7
	s_cbranch_scc1 .Lsel1_done
	v_ashrrev_i32_e32 v66, 31, v30
	v_or_b32_e32 v66, 0x80000000, v66
	v_xor_b32_e32 v30, v30, v66
	v_bfe_u32 v30, v30, 20, 12
	v_lshl_add_u32 v30, v30, 2, s33
	ds_add_u32 v30, v225
	v_ashrrev_i32_e32 v67, 31, v31
	v_or_b32_e32 v67, 0x80000000, v67
	v_xor_b32_e32 v31, v31, v67
	v_bfe_u32 v31, v31, 20, 12
	v_lshl_add_u32 v31, v31, 2, s33
	ds_add_u32 v31, v225
	v_ashrrev_i32_e32 v66, 31, v32
	v_or_b32_e32 v66, 0x80000000, v66
	v_xor_b32_e32 v32, v32, v66
	v_bfe_u32 v32, v32, 20, 12
	v_lshl_add_u32 v32, v32, 2, s33
	ds_add_u32 v32, v225
	v_ashrrev_i32_e32 v67, 31, v33
	v_or_b32_e32 v67, 0x80000000, v67
	v_xor_b32_e32 v33, v33, v67
	v_bfe_u32 v33, v33, 20, 12
	v_lshl_add_u32 v33, v33, 2, s33
	ds_add_u32 v33, v225
	s_cmp_eq_u32 s1, 8
	s_cbranch_scc1 .Lsel1_done
	v_ashrrev_i32_e32 v66, 31, v26
	v_or_b32_e32 v66, 0x80000000, v66
	v_xor_b32_e32 v26, v26, v66
	v_bfe_u32 v26, v26, 20, 12
	v_lshl_add_u32 v26, v26, 2, s33
	ds_add_u32 v26, v225
	v_ashrrev_i32_e32 v67, 31, v27
	v_or_b32_e32 v67, 0x80000000, v67
	v_xor_b32_e32 v27, v27, v67
	v_bfe_u32 v27, v27, 20, 12
	v_lshl_add_u32 v27, v27, 2, s33
	ds_add_u32 v27, v225
	v_ashrrev_i32_e32 v66, 31, v28
	v_or_b32_e32 v66, 0x80000000, v66
	v_xor_b32_e32 v28, v28, v66
	v_bfe_u32 v28, v28, 20, 12
	v_lshl_add_u32 v28, v28, 2, s33
	ds_add_u32 v28, v225
	v_ashrrev_i32_e32 v67, 31, v29
	v_or_b32_e32 v67, 0x80000000, v67
	v_xor_b32_e32 v29, v29, v67
	v_bfe_u32 v29, v29, 20, 12
	v_lshl_add_u32 v29, v29, 2, s33
	ds_add_u32 v29, v225
	s_cmp_eq_u32 s1, 9
	s_cbranch_scc1 .Lsel1_done
	v_ashrrev_i32_e32 v66, 31, v22
	v_or_b32_e32 v66, 0x80000000, v66
	v_xor_b32_e32 v22, v22, v66
	v_bfe_u32 v22, v22, 20, 12
	v_lshl_add_u32 v22, v22, 2, s33
	ds_add_u32 v22, v225
	v_ashrrev_i32_e32 v67, 31, v23
	v_or_b32_e32 v67, 0x80000000, v67
	v_xor_b32_e32 v23, v23, v67
	v_bfe_u32 v23, v23, 20, 12
	v_lshl_add_u32 v23, v23, 2, s33
	ds_add_u32 v23, v225
	v_ashrrev_i32_e32 v66, 31, v24
	v_or_b32_e32 v66, 0x80000000, v66
	v_xor_b32_e32 v24, v24, v66
	v_bfe_u32 v24, v24, 20, 12
	v_lshl_add_u32 v24, v24, 2, s33
	ds_add_u32 v24, v225
	v_ashrrev_i32_e32 v67, 31, v25
	v_or_b32_e32 v67, 0x80000000, v67
	v_xor_b32_e32 v25, v25, v67
	v_bfe_u32 v25, v25, 20, 12
	v_lshl_add_u32 v25, v25, 2, s33
	ds_add_u32 v25, v225
	s_cmp_eq_u32 s1, 10
	s_cbranch_scc1 .Lsel1_done
	v_ashrrev_i32_e32 v66, 31, v18
	v_or_b32_e32 v66, 0x80000000, v66
	v_xor_b32_e32 v18, v18, v66
	v_bfe_u32 v18, v18, 20, 12
	v_lshl_add_u32 v18, v18, 2, s33
	ds_add_u32 v18, v225
	v_ashrrev_i32_e32 v67, 31, v19
	v_or_b32_e32 v67, 0x80000000, v67
	v_xor_b32_e32 v19, v19, v67
	v_bfe_u32 v19, v19, 20, 12
	v_lshl_add_u32 v19, v19, 2, s33
	ds_add_u32 v19, v225
	v_ashrrev_i32_e32 v66, 31, v20
	v_or_b32_e32 v66, 0x80000000, v66
	v_xor_b32_e32 v20, v20, v66
	v_bfe_u32 v20, v20, 20, 12
	v_lshl_add_u32 v20, v20, 2, s33
	ds_add_u32 v20, v225
	v_ashrrev_i32_e32 v67, 31, v21
	v_or_b32_e32 v67, 0x80000000, v67
	v_xor_b32_e32 v21, v21, v67
	v_bfe_u32 v21, v21, 20, 12
	v_lshl_add_u32 v21, v21, 2, s33
	ds_add_u32 v21, v225
	s_cmp_eq_u32 s1, 11
	s_cbranch_scc1 .Lsel1_done
	v_ashrrev_i32_e32 v66, 31, v14
	v_or_b32_e32 v66, 0x80000000, v66
	v_xor_b32_e32 v14, v14, v66
	v_bfe_u32 v14, v14, 20, 12
	v_lshl_add_u32 v14, v14, 2, s33
	ds_add_u32 v14, v225
	v_ashrrev_i32_e32 v67, 31, v15
	v_or_b32_e32 v67, 0x80000000, v67
	v_xor_b32_e32 v15, v15, v67
	v_bfe_u32 v15, v15, 20, 12
	v_lshl_add_u32 v15, v15, 2, s33
	ds_add_u32 v15, v225
	v_ashrrev_i32_e32 v66, 31, v16
	v_or_b32_e32 v66, 0x80000000, v66
	v_xor_b32_e32 v16, v16, v66
	v_bfe_u32 v16, v16, 20, 12
	v_lshl_add_u32 v16, v16, 2, s33
	ds_add_u32 v16, v225
	v_ashrrev_i32_e32 v67, 31, v17
	v_or_b32_e32 v67, 0x80000000, v67
	v_xor_b32_e32 v17, v17, v67
	v_bfe_u32 v17, v17, 20, 12
	v_lshl_add_u32 v17, v17, 2, s33
	ds_add_u32 v17, v225
	s_cmp_eq_u32 s1, 12
	s_cbranch_scc1 .Lsel1_done
	v_ashrrev_i32_e32 v66, 31, v10
	v_or_b32_e32 v66, 0x80000000, v66
	v_xor_b32_e32 v10, v10, v66
	v_bfe_u32 v10, v10, 20, 12
	v_lshl_add_u32 v10, v10, 2, s33
	ds_add_u32 v10, v225
	v_ashrrev_i32_e32 v67, 31, v11
	v_or_b32_e32 v67, 0x80000000, v67
	v_xor_b32_e32 v11, v11, v67
	v_bfe_u32 v11, v11, 20, 12
	v_lshl_add_u32 v11, v11, 2, s33
	ds_add_u32 v11, v225
	v_ashrrev_i32_e32 v66, 31, v12
	v_or_b32_e32 v66, 0x80000000, v66
	v_xor_b32_e32 v12, v12, v66
	v_bfe_u32 v12, v12, 20, 12
	v_lshl_add_u32 v12, v12, 2, s33
	ds_add_u32 v12, v225
	v_ashrrev_i32_e32 v67, 31, v13
	v_or_b32_e32 v67, 0x80000000, v67
	v_xor_b32_e32 v13, v13, v67
	v_bfe_u32 v13, v13, 20, 12
	v_lshl_add_u32 v13, v13, 2, s33
	ds_add_u32 v13, v225
	s_cmp_eq_u32 s1, 13
	s_cbranch_scc1 .Lsel1_done
	v_ashrrev_i32_e32 v66, 31, v6
	v_or_b32_e32 v66, 0x80000000, v66
	v_xor_b32_e32 v6, v6, v66
	v_bfe_u32 v6, v6, 20, 12
	v_lshl_add_u32 v6, v6, 2, s33
	ds_add_u32 v6, v225
	v_ashrrev_i32_e32 v67, 31, v7
	v_or_b32_e32 v67, 0x80000000, v67
	v_xor_b32_e32 v7, v7, v67
	v_bfe_u32 v7, v7, 20, 12
	v_lshl_add_u32 v7, v7, 2, s33
	ds_add_u32 v7, v225
	v_ashrrev_i32_e32 v66, 31, v8
	v_or_b32_e32 v66, 0x80000000, v66
	v_xor_b32_e32 v8, v8, v66
	v_bfe_u32 v8, v8, 20, 12
	v_lshl_add_u32 v8, v8, 2, s33
	ds_add_u32 v8, v225
	v_ashrrev_i32_e32 v67, 31, v9
	v_or_b32_e32 v67, 0x80000000, v67
	v_xor_b32_e32 v9, v9, v67
	v_bfe_u32 v9, v9, 20, 12
	v_lshl_add_u32 v9, v9, 2, s33
	ds_add_u32 v9, v225
	s_cmp_eq_u32 s1, 14
	s_cbranch_scc1 .Lsel1_done
	v_ashrrev_i32_e32 v66, 31, v2
	v_or_b32_e32 v66, 0x80000000, v66
	v_xor_b32_e32 v2, v2, v66
	v_bfe_u32 v2, v2, 20, 12
	v_lshl_add_u32 v2, v2, 2, s33
	ds_add_u32 v2, v225
	v_ashrrev_i32_e32 v67, 31, v3
	v_or_b32_e32 v67, 0x80000000, v67
	v_xor_b32_e32 v3, v3, v67
	v_bfe_u32 v3, v3, 20, 12
	v_lshl_add_u32 v3, v3, 2, s33
	ds_add_u32 v3, v225
	v_ashrrev_i32_e32 v66, 31, v4
	v_or_b32_e32 v66, 0x80000000, v66
	v_xor_b32_e32 v4, v4, v66
	v_bfe_u32 v4, v4, 20, 12
	v_lshl_add_u32 v4, v4, 2, s33
	ds_add_u32 v4, v225
	v_ashrrev_i32_e32 v67, 31, v5
	v_or_b32_e32 v67, 0x80000000, v67
	v_xor_b32_e32 v5, v5, v67
	v_bfe_u32 v5, v5, 20, 12
	v_lshl_add_u32 v5, v5, 2, s33
	ds_add_u32 v5, v225
.Lsel1_done:
	s_addk_i32 s10, 0x1000
	s_cmp_lt_u32 s10, s27
	s_cbranch_scc1 .LBB0_582

; __device__ __forceinline__ unsigned f2key(float f) { const unsigned u = __float_as_uint(f); return (u & 0x80000000u) ? ~u : (u | 0x80000000u); }
; #define MK_HADD(p) __hip_atomic_fetch_add((p), 1u, __ATOMIC_RELAXED, __HIP_MEMORY_SCOPE_WORKGROUP)
; #define SEL_LOAD4(v_, i0_) do { _Pragma("unroll") for (int q = 0; q < 16; ++q) { const int i_ = (i0_) + 256 * q + 4 * lane; v_[q] = (i_ < n) ? srow4[i_ >> 2] : (f32x4){0.f, 0.f, 0.f, 0.f}; } } while (0)
; __device__ __forceinline__ void select256(LAS unsigned char* wl, const float* srow, int n, int lane) {
;     ...
;     hist_zero<4096>(hist, lane);
;     for (int i0 = 0; i0 < n; i0 += 4096) {
;         f32x4 v[16]; SEL_LOAD4(v, i0);
; #pragma unroll
;         for (int q = 0; q < 16; ++q)
; #pragma unroll
;             for (int e = 0; e < 4; ++e) { const int i = i0 + 256 * q + 4 * lane + e; if (i < n) MK_HADD(hist + (f2key(v[q][e]) >> 20)); }
;     }
;     const unsigned b1 = find_bin<12>(hist, k, lane);
;     unsigned run = 0, cc = 0;
;     for (int i0 = 0; i0 < n; i0 += 4096) {
;         f32x4 v[16]; SEL_LOAD4(v, i0);
; #pragma unroll
;         for (int q = 0; q < 16; ++q)
; #pragma unroll
;             for (int e = 0; e < 4; ++e) {
;                 const int i = i0 + 256 * q + 4 * lane + e; const bool in = i < n; const unsigned key = f2key(v[q][e]); const unsigned bin = key >> 20;
.LBB0_753:
	s_sub_u32 s0, s70, s38
	s_lshr_b32 s1, s0, 8
	v_add_u32_e32 v73, s38, v133
	v_lshlrev_b32_e32 v74, 2, v73
	s_add_u32 s74, s30, 0x1000
	s_addc_u32 s75, s31, 0
	s_add_u32 s76, s30, 0x2000
	s_addc_u32 s77, s31, 0
	s_add_u32 s78, s30, 0x3000
	s_addc_u32 s79, s31, 0
	s_cmp_gt_u32 s1, 0
	s_cbranch_scc1 .Lsel2_full_0
	v_mov_b32_e32 v62, -1
	v_mov_b32_e32 v63, -1
	v_mov_b32_e32 v64, -1
	v_mov_b32_e32 v65, -1
	v_mov_b32_e32 v79, v73
	v_cmp_ge_i32_e32 vcc, s70, v79
	s_mov_b64 exec, vcc
	global_load_dwordx4 v[62:65], v74, s[30:31]
	s_mov_b64 exec, -1
	v_sub_u32_e32 v80, s70, v79
	v_cmp_gt_i32_e64 s[4:5], 1, v80
	v_cmp_gt_i32_e64 s[6:7], 2, v80
	v_cmp_gt_i32_e64 s[10:11], 3, v80
	s_waitcnt vmcnt(0)
	v_cndmask_b32_e64 v63, v63, -1, s[4:5]
	v_cndmask_b32_e64 v64, v64, -1, s[6:7]
	v_cndmask_b32_e64 v65, v65, -1, s[10:11]
	s_branch .Lsel2_proc
.Lsel2_full_0:
	global_load_dwordx4 v[62:65], v74, s[30:31]
	s_cmp_gt_u32 s1, 1
	s_cbranch_scc1 .Lsel2_full_1
	v_mov_b32_e32 v58, -1
	v_mov_b32_e32 v59, -1
	v_mov_b32_e32 v60, -1
	v_mov_b32_e32 v61, -1
	v_add_u32_e32 v79, 0x100, v73
	v_cmp_ge_i32_e32 vcc, s70, v79
	s_mov_b64 exec, vcc
	global_load_dwordx4 v[58:61], v74, s[30:31] offset:1024
	s_mov_b64 exec, -1
	v_sub_u32_e32 v80, s70, v79
	v_cmp_gt_i32_e64 s[4:5], 1, v80
	v_cmp_gt_i32_e64 s[6:7], 2, v80
	v_cmp_gt_i32_e64 s[10:11], 3, v80
	s_waitcnt vmcnt(0)
	v_cndmask_b32_e64 v59, v59, -1, s[4:5]
	v_cndmask_b32_e64 v60, v60, -1, s[6:7]
	v_cndmask_b32_e64 v61, v61, -1, s[10:11]
	s_branch .Lsel2_proc
.Lsel2_full_1:
	global_load_dwordx4 v[58:61], v74, s[30:31] offset:1024
	s_cmp_gt_u32 s1, 2
	s_cbranch_scc1 .Lsel2_full_2
	v_mov_b32_e32 v54, -1
	v_mov_b32_e32 v55, -1
	v_mov_b32_e32 v56, -1
	v_mov_b32_e32 v57, -1
	v_add_u32_e32 v79, 0x200, v73
	v_cmp_ge_i32_e32 vcc, s70, v79
	s_mov_b64 exec, vcc
	global_load_dwordx4 v[54:57], v74, s[30:31] offset:2048
	s_mov_b64 exec, -1
	v_sub_u32_e32 v80, s70, v79
	v_cmp_gt_i32_e64 s[4:5], 1, v80
	v_cmp_gt_i32_e64 s[6:7], 2, v80
	v_cmp_gt_i32_e64 s[10:11], 3, v80
	s_waitcnt vmcnt(0)
	v_cndmask_b32_e64 v55, v55, -1, s[4:5]
	v_cndmask_b32_e64 v56, v56, -1, s[6:7]
	v_cndmask_b32_e64 v57, v57, -1, s[10:11]
	s_branch .Lsel2_proc
.Lsel2_full_2:
	global_load_dwordx4 v[54:57], v74, s[30:31] offset:2048
	s_cmp_gt_u32 s1, 3
	s_cbranch_scc1 .Lsel2_full_3
	v_mov_b32_e32 v50, -1
	v_mov_b32_e32 v51, -1
	v_mov_b32_e32 v52, -1
	v_mov_b32_e32 v53, -1
	v_add_u32_e32 v79, 0x300, v73
	v_cmp_ge_i32_e32 vcc, s70, v79
	s_mov_b64 exec, vcc
	global_load_dwordx4 v[50:53], v74, s[30:31] offset:3072
	s_mov_b64 exec, -1
	v_sub_u32_e32 v80, s70, v79
	v_cmp_gt_i32_e64 s[4:5], 1, v80
	v_cmp_gt_i32_e64 s[6:7], 2, v80
	v_cmp_gt_i32_e64 s[10:11], 3, v80
	s_waitcnt vmcnt(0)
	v_cndmask_b32_e64 v51, v51, -1, s[4:5]
	v_cndmask_b32_e64 v52, v52, -1, s[6:7]
	v_cndmask_b32_e64 v53, v53, -1, s[10:11]
	s_branch .Lsel2_proc
.Lsel2_full_3:
	global_load_dwordx4 v[50:53], v74, s[30:31] offset:3072
	s_cmp_gt_u32 s1, 4
	s_cbranch_scc1 .Lsel2_full_4
	v_mov_b32_e32 v46, -1
	v_mov_b32_e32 v47, -1
	v_mov_b32_e32 v48, -1
	v_mov_b32_e32 v49, -1
	v_add_u32_e32 v79, 0x400, v73
	v_cmp_ge_i32_e32 vcc, s70, v79
	s_mov_b64 exec, vcc
	global_load_dwordx4 v[46:49], v74, s[74:75]
	s_mov_b64 exec, -1
	v_sub_u32_e32 v80, s70, v79
	v_cmp_gt_i32_e64 s[4:5], 1, v80
	v_cmp_gt_i32_e64 s[6:7], 2, v80
	v_cmp_gt_i32_e64 s[10:11], 3, v80
	s_waitcnt vmcnt(0)
	v_cndmask_b32_e64 v47, v47, -1, s[4:5]
	v_cndmask_b32_e64 v48, v48, -1, s[6:7]
	v_cndmask_b32_e64 v49, v49, -1, s[10:11]
	s_branch .Lsel2_proc
.Lsel2_full_4:
	global_load_dwordx4 v[46:49], v74, s[74:75]
	s_cmp_gt_u32 s1, 5
	s_cbranch_scc1 .Lsel2_full_5
	v_mov_b32_e32 v42, -1
	v_mov_b32_e32 v43, -1
	v_mov_b32_e32 v44, -1
	v_mov_b32_e32 v45, -1
	v_add_u32_e32 v79, 0x500, v73
	v_cmp_ge_i32_e32 vcc, s70, v79
	s_mov_b64 exec, vcc
	global_load_dwordx4 v[42:45], v74, s[74:75] offset:1024
	s_mov_b64 exec, -1
	v_sub_u32_e32 v80, s70, v79
	v_cmp_gt_i32_e64 s[4:5], 1, v80
	v_cmp_gt_i32_e64 s[6:7], 2, v80
	v_cmp_gt_i32_e64 s[10:11], 3, v80
	s_waitcnt vmcnt(0)
	v_cndmask_b32_e64 v43, v43, -1, s[4:5]
	v_cndmask_b32_e64 v44, v44, -1, s[6:7]
	v_cndmask_b32_e64 v45, v45, -1, s[10:11]
	s_branch .Lsel2_proc
.Lsel2_full_5:
	global_load_dwordx4 v[42:45], v74, s[74:75] offset:1024
	s_cmp_gt_u32 s1, 6
	s_cbranch_scc1 .Lsel2_full_6
	v_mov_b32_e32 v38, -1
	v_mov_b32_e32 v39, -1
	v_mov_b32_e32 v40, -1
	v_mov_b32_e32 v41, -1
	v_add_u32_e32 v79, 0x600, v73
	v_cmp_ge_i32_e32 vcc, s70, v79
	s_mov_b64 exec, vcc
	global_load_dwordx4 v[38:41], v74, s[74:75] offset:2048
	s_mov_b64 exec, -1
	v_sub_u32_e32 v80, s70, v79
	v_cmp_gt_i32_e64 s[4:5], 1, v80
	v_cmp_gt_i32_e64 s[6:7], 2, v80
	v_cmp_gt_i32_e64 s[10:11], 3, v80
	s_waitcnt vmcnt(0)
	v_cndmask_b32_e64 v39, v39, -1, s[4:5]
	v_cndmask_b32_e64 v40, v40, -1, s[6:7]
	v_cndmask_b32_e64 v41, v41, -1, s[10:11]
	s_branch .Lsel2_proc
.Lsel2_full_6:
	global_load_dwordx4 v[38:41], v74, s[74:75] offset:2048
	s_cmp_gt_u32 s1, 7
	s_cbranch_scc1 .Lsel2_full_7
	v_mov_b32_e32 v34, -1
	v_mov_b32_e32 v35, -1
	v_mov_b32_e32 v36, -1
	v_mov_b32_e32 v37, -1
	v_add_u32_e32 v79, 0x700, v73
	v_cmp_ge_i32_e32 vcc, s70, v79
	s_mov_b64 exec, vcc
	global_load_dwordx4 v[34:37], v74, s[74:75] offset:3072
	s_mov_b64 exec, -1
	v_sub_u32_e32 v80, s70, v79
	v_cmp_gt_i32_e64 s[4:5], 1, v80
	v_cmp_gt_i32_e64 s[6:7], 2, v80
	v_cmp_gt_i32_e64 s[10:11], 3, v80
	s_waitcnt vmcnt(0)
	v_cndmask_b32_e64 v35, v35, -1, s[4:5]
	v_cndmask_b32_e64 v36, v36, -1, s[6:7]
	v_cndmask_b32_e64 v37, v37, -1, s[10:11]
	s_branch .Lsel2_proc
; __device__ __forceinline__ unsigned f2key(float f) { const unsigned u = __float_as_uint(f); return (u & 0x80000000u) ? ~u : (u | 0x80000000u); }
; #define MK_HADD(p) __hip_atomic_fetch_add((p), 1u, __ATOMIC_RELAXED, __HIP_MEMORY_SCOPE_WORKGROUP)
; #define SEL_LOAD4(v_, i0_) do { _Pragma("unroll") for (int q = 0; q < 16; ++q) { const int i_ = (i0_) + 256 * q + 4 * lane; v_[q] = (i_ < n) ? srow4[i_ >> 2] : (f32x4){0.f, 0.f, 0.f, 0.f}; } } while (0)
; __device__ __forceinline__ void select256(LAS unsigned char* wl, const float* srow, int n, int lane) {
;     ...
;     hist_zero<4096>(hist, lane);
;     for (int i0 = 0; i0 < n; i0 += 4096) {
;         f32x4 v[16]; SEL_LOAD4(v, i0);
; #pragma unroll
;         for (int q = 0; q < 16; ++q)
; #pragma unroll
;             for (int e = 0; e < 4; ++e) { const int i = i0 + 256 * q + 4 * lane + e; if (i < n) MK_HADD(hist + (f2key(v[q][e]) >> 20)); }
;     }
;     const unsigned b1 = find_bin<12>(hist, k, lane);
;     unsigned run = 0, cc = 0;
;     for (int i0 = 0; i0 < n; i0 += 4096) {
;         f32x4 v[16]; SEL_LOAD4(v, i0);
; #pragma unroll
;         for (int q = 0; q < 16; ++q)
; #pragma unroll
;             for (int e = 0; e < 4; ++e) {
;                 const int i = i0 + 256 * q + 4 * lane + e; const bool in = i < n; const unsigned key = f2key(v[q][e]); const unsigned bin = key >> 20;
.Lsel2_full_7:
	global_load_dwordx4 v[34:37], v74, s[74:75] offset:3072
	s_cmp_gt_u32 s1, 8
	s_cbranch_scc1 .Lsel2_full_8
	v_mov_b32_e32 v30, -1
	v_mov_b32_e32 v31, -1
	v_mov_b32_e32 v32, -1
	v_mov_b32_e32 v33, -1
	v_add_u32_e32 v79, 0x800, v73
	v_cmp_ge_i32_e32 vcc, s70, v79
	s_mov_b64 exec, vcc
	global_load_dwordx4 v[30:33], v74, s[76:77]
	s_mov_b64 exec, -1
	v_sub_u32_e32 v80, s70, v79
	v_cmp_gt_i32_e64 s[4:5], 1, v80
	v_cmp_gt_i32_e64 s[6:7], 2, v80
	v_cmp_gt_i32_e64 s[10:11], 3, v80
	s_waitcnt vmcnt(0)
	v_cndmask_b32_e64 v31, v31, -1, s[4:5]
	v_cndmask_b32_e64 v32, v32, -1, s[6:7]
	v_cndmask_b32_e64 v33, v33, -1, s[10:11]
	s_branch .Lsel2_proc
.Lsel2_full_8:
	global_load_dwordx4 v[30:33], v74, s[76:77]
	s_cmp_gt_u32 s1, 9
	s_cbranch_scc1 .Lsel2_full_9
	v_mov_b32_e32 v26, -1
	v_mov_b32_e32 v27, -1
	v_mov_b32_e32 v28, -1
	v_mov_b32_e32 v29, -1
	v_add_u32_e32 v79, 0x900, v73
	v_cmp_ge_i32_e32 vcc, s70, v79
	s_mov_b64 exec, vcc
	global_load_dwordx4 v[26:29], v74, s[76:77] offset:1024
	s_mov_b64 exec, -1
	v_sub_u32_e32 v80, s70, v79
	v_cmp_gt_i32_e64 s[4:5], 1, v80
	v_cmp_gt_i32_e64 s[6:7], 2, v80
	v_cmp_gt_i32_e64 s[10:11], 3, v80
	s_waitcnt vmcnt(0)
	v_cndmask_b32_e64 v27, v27, -1, s[4:5]
	v_cndmask_b32_e64 v28, v28, -1, s[6:7]
	v_cndmask_b32_e64 v29, v29, -1, s[10:11]
	s_branch .Lsel2_proc
.Lsel2_full_9:
	global_load_dwordx4 v[26:29], v74, s[76:77] offset:1024
	s_cmp_gt_u32 s1, 10
	s_cbranch_scc1 .Lsel2_full_10
	v_mov_b32_e32 v22, -1
	v_mov_b32_e32 v23, -1
	v_mov_b32_e32 v24, -1
	v_mov_b32_e32 v25, -1
	v_add_u32_e32 v79, 0xa00, v73
	v_cmp_ge_i32_e32 vcc, s70, v79
	s_mov_b64 exec, vcc
	global_load_dwordx4 v[22:25], v74, s[76:77] offset:2048
	s_mov_b64 exec, -1
	v_sub_u32_e32 v80, s70, v79
	v_cmp_gt_i32_e64 s[4:5], 1, v80
	v_cmp_gt_i32_e64 s[6:7], 2, v80
	v_cmp_gt_i32_e64 s[10:11], 3, v80
	s_waitcnt vmcnt(0)
	v_cndmask_b32_e64 v23, v23, -1, s[4:5]
	v_cndmask_b32_e64 v24, v24, -1, s[6:7]
	v_cndmask_b32_e64 v25, v25, -1, s[10:11]
	s_branch .Lsel2_proc
.Lsel2_full_10:
	global_load_dwordx4 v[22:25], v74, s[76:77] offset:2048
	s_cmp_gt_u32 s1, 11
	s_cbranch_scc1 .Lsel2_full_11
	v_mov_b32_e32 v18, -1
	v_mov_b32_e32 v19, -1
	v_mov_b32_e32 v20, -1
	v_mov_b32_e32 v21, -1
	v_add_u32_e32 v79, 0xb00, v73
	v_cmp_ge_i32_e32 vcc, s70, v79
	s_mov_b64 exec, vcc
	global_load_dwordx4 v[18:21], v74, s[76:77] offset:3072
	s_mov_b64 exec, -1
	v_sub_u32_e32 v80, s70, v79
	v_cmp_gt_i32_e64 s[4:5], 1, v80
	v_cmp_gt_i32_e64 s[6:7], 2, v80
	v_cmp_gt_i32_e64 s[10:11], 3, v80
	s_waitcnt vmcnt(0)
	v_cndmask_b32_e64 v19, v19, -1, s[4:5]
	v_cndmask_b32_e64 v20, v20, -1, s[6:7]
	v_cndmask_b32_e64 v21, v21, -1, s[10:11]
	s_branch .Lsel2_proc
.Lsel2_full_11:
	global_load_dwordx4 v[18:21], v74, s[76:77] offset:3072
	s_cmp_gt_u32 s1, 12
	s_cbranch_scc1 .Lsel2_full_12
	v_mov_b32_e32 v14, -1
	v_mov_b32_e32 v15, -1
	v_mov_b32_e32 v16, -1
	v_mov_b32_e32 v17, -1
	v_add_u32_e32 v79, 0xc00, v73
	v_cmp_ge_i32_e32 vcc, s70, v79
	s_mov_b64 exec, vcc
	global_load_dwordx4 v[14:17], v74, s[78:79]
	s_mov_b64 exec, -1
	v_sub_u32_e32 v80, s70, v79
	v_cmp_gt_i32_e64 s[4:5], 1, v80
	v_cmp_gt_i32_e64 s[6:7], 2, v80
	v_cmp_gt_i32_e64 s[10:11], 3, v80
	s_waitcnt vmcnt(0)
	v_cndmask_b32_e64 v15, v15, -1, s[4:5]
	v_cndmask_b32_e64 v16, v16, -1, s[6:7]
	v_cndmask_b32_e64 v17, v17, -1, s[10:11]
	s_branch .Lsel2_proc
.Lsel2_full_12:
	global_load_dwordx4 v[14:17], v74, s[78:79]
	s_cmp_gt_u32 s1, 13
	s_cbranch_scc1 .Lsel2_full_13
	v_mov_b32_e32 v10, -1
	v_mov_b32_e32 v11, -1
	v_mov_b32_e32 v12, -1
	v_mov_b32_e32 v13, -1
	v_add_u32_e32 v79, 0xd00, v73
	v_cmp_ge_i32_e32 vcc, s70, v79
	s_mov_b64 exec, vcc
	global_load_dwordx4 v[10:13], v74, s[78:79] offset:1024
	s_mov_b64 exec, -1
	v_sub_u32_e32 v80, s70, v79
	v_cmp_gt_i32_e64 s[4:5], 1, v80
	v_cmp_gt_i32_e64 s[6:7], 2, v80
	v_cmp_gt_i32_e64 s[10:11], 3, v80
	s_waitcnt vmcnt(0)
	v_cndmask_b32_e64 v11, v11, -1, s[4:5]
	v_cndmask_b32_e64 v12, v12, -1, s[6:7]
	v_cndmask_b32_e64 v13, v13, -1, s[10:11]
	s_branch .Lsel2_proc
.Lsel2_full_13:
	global_load_dwordx4 v[10:13], v74, s[78:79] offset:1024
	s_cmp_gt_u32 s1, 14
	s_cbranch_scc1 .Lsel2_full_14
	v_mov_b32_e32 v6, -1
	v_mov_b32_e32 v7, -1
	v_mov_b32_e32 v8, -1
	v_mov_b32_e32 v9, -1
	v_add_u32_e32 v79, 0xe00, v73
	v_cmp_ge_i32_e32 vcc, s70, v79
	s_mov_b64 exec, vcc
	global_load_dwordx4 v[6:9], v74, s[78:79] offset:2048
	s_mov_b64 exec, -1
	v_sub_u32_e32 v80, s70, v79
	v_cmp_gt_i32_e64 s[4:5], 1, v80
	v_cmp_gt_i32_e64 s[6:7], 2, v80
	v_cmp_gt_i32_e64 s[10:11], 3, v80
	s_waitcnt vmcnt(0)
	v_cndmask_b32_e64 v7, v7, -1, s[4:5]
	v_cndmask_b32_e64 v8, v8, -1, s[6:7]
	v_cndmask_b32_e64 v9, v9, -1, s[10:11]
	s_branch .Lsel2_proc
.Lsel2_full_14:
	global_load_dwordx4 v[6:9], v74, s[78:79] offset:2048
	s_cmp_gt_u32 s1, 15
	s_cbranch_scc1 .Lsel2_full_15
	v_mov_b32_e32 v2, -1
	v_mov_b32_e32 v3, -1
	v_mov_b32_e32 v4, -1
	v_mov_b32_e32 v5, -1
	v_add_u32_e32 v79, 0xf00, v73
	v_cmp_ge_i32_e32 vcc, s70, v79
	s_mov_b64 exec, vcc
	global_load_dwordx4 v[2:5], v74, s[78:79] offset:3072
	s_mov_b64 exec, -1
	v_sub_u32_e32 v80, s70, v79
	v_cmp_gt_i32_e64 s[4:5], 1, v80
	v_cmp_gt_i32_e64 s[6:7], 2, v80
	v_cmp_gt_i32_e64 s[10:11], 3, v80
	s_waitcnt vmcnt(0)
	v_cndmask_b32_e64 v3, v3, -1, s[4:5]
	v_cndmask_b32_e64 v4, v4, -1, s[6:7]
	v_cndmask_b32_e64 v5, v5, -1, s[10:11]
	s_branch .Lsel2_proc
.Lsel2_full_15:
	global_load_dwordx4 v[2:5], v74, s[78:79] offset:3072
	s_waitcnt vmcnt(0)
; __device__ __forceinline__ unsigned f2key(float f) { const unsigned u = __float_as_uint(f); return (u & 0x80000000u) ? ~u : (u | 0x80000000u); }
; #define SEL_LOAD4(v_, i0_) do { _Pragma("unroll") for (int q = 0; q < 16; ++q) { const int i_ = (i0_) + 256 * q + 4 * lane; v_[q] = (i_ < n) ? srow4[i_ >> 2] : (f32x4){0.f, 0.f, 0.f, 0.f}; } } while (0)
; __device__ __forceinline__ void select256(LAS unsigned char* wl, const float* srow, int n, int lane) {
;     ...
;     for (int i0 = 0; i0 < n; i0 += 4096) {
;         f32x4 v[16]; SEL_LOAD4(v, i0);
; #pragma unroll
;         for (int q = 0; q < 16; ++q)
; #pragma unroll
;             for (int e = 0; e < 4; ++e) {
;                 const int i = i0 + 256 * q + 4 * lane + e; const bool in = i < n; const unsigned key = f2key(v[q][e]); const unsigned bin = key >> 20;
;                 const bool gt = in && bin > b1, eq = in && bin == b1;
;                 const unsigned long long bg = __ballot(gt), be = __ballot(eq);
;                 if (gt) { const unsigned pos = run + (unsigned)__popcll(bg & lt); if (pos < 256u) idx[pos] = i; }
;                 if (eq) { const unsigned pos = cc + (unsigned)__popcll(be & lt); if (pos < (unsigned)CAP) { candk[pos] = key; candi[pos] = i; } }
;                 run += (unsigned)__popcll(bg); cc += (unsigned)__popcll(be);
;             }
;     }
.Lsel2_proc:
	s_lshl2_add_u32 s42, s24, s33
	s_min_u32 s8, s39, 0xbc0
	s_lshl2_add_u32 s44, s8, s33
	v_mov_b32_e32 v79, v73
	v_ashrrev_i32_e32 v75, 31, v62
	v_or_b32_e32 v75, 0x80000000, v75
	v_xor_b32_e32 v62, v62, v75
	v_lshrrev_b32_e32 v75, 20, v62
	v_cmp_lt_u32_e64 s[4:5], s73, v75
	v_cmp_eq_u32_e64 s[6:7], s73, v75
	s_bcnt1_i32_b64 s8, s[4:5]
	v_mbcnt_lo_u32_b32 v77, s4, 0
	v_mbcnt_hi_u32_b32 v77, s5, v77
	v_lshl_add_u32 v77, v77, 2, s42
	s_mov_b64 exec, s[4:5]
	ds_write_b32 v77, v79 offset:16384
	s_mov_b64 exec, s[6:7]
	v_mbcnt_lo_u32_b32 v78, s6, 0
	v_mbcnt_hi_u32_b32 v78, s7, v78
	v_lshl_add_u32 v78, v78, 2, s44
	ds_write2st64_b32 v78, v62, v79 offset1:16
	s_mov_b64 exec, -1
	s_add_u32 s24, s24, s8
	s_lshl2_add_u32 s42, s8, s42
	s_bcnt1_i32_b64 s9, s[6:7]
	s_add_u32 s39, s39, s9
	s_min_u32 s9, s39, 0xbc0
	s_lshl2_add_u32 s44, s9, s33
	v_ashrrev_i32_e32 v80, 31, v63
	v_or_b32_e32 v80, 0x80000000, v80
	v_xor_b32_e32 v63, v63, v80
	v_lshrrev_b32_e32 v80, 20, v63
	v_cmp_lt_u32_e64 s[10:11], s73, v80
	v_cmp_eq_u32_e64 s[14:15], s73, v80
	v_or_b32_e32 v81, 1, v79
	s_bcnt1_i32_b64 s8, s[10:11]
	v_mbcnt_lo_u32_b32 v82, s10, 0
	v_mbcnt_hi_u32_b32 v82, s11, v82
	v_lshl_add_u32 v82, v82, 2, s42
	s_mov_b64 exec, s[10:11]
	ds_write_b32 v82, v81 offset:16384
	s_mov_b64 exec, s[14:15]
	v_mbcnt_lo_u32_b32 v83, s14, 0
	v_mbcnt_hi_u32_b32 v83, s15, v83
	v_lshl_add_u32 v83, v83, 2, s44
	ds_write2st64_b32 v83, v63, v81 offset1:16
	s_mov_b64 exec, -1
	s_add_u32 s24, s24, s8
	s_lshl2_add_u32 s42, s8, s42
	s_bcnt1_i32_b64 s9, s[14:15]
	s_add_u32 s39, s39, s9
	s_min_u32 s9, s39, 0xbc0
	s_lshl2_add_u32 s44, s9, s33
	v_ashrrev_i32_e32 v75, 31, v64
	v_or_b32_e32 v75, 0x80000000, v75
	v_xor_b32_e32 v64, v64, v75
	v_lshrrev_b32_e32 v75, 20, v64
	v_cmp_lt_u32_e64 s[4:5], s73, v75
	v_cmp_eq_u32_e64 s[6:7], s73, v75
	v_or_b32_e32 v76, 2, v79
	s_bcnt1_i32_b64 s8, s[4:5]
	v_mbcnt_lo_u32_b32 v77, s4, 0
	v_mbcnt_hi_u32_b32 v77, s5, v77
	v_lshl_add_u32 v77, v77, 2, s42
	s_mov_b64 exec, s[4:5]
	ds_write_b32 v77, v76 offset:16384
	s_mov_b64 exec, s[6:7]
	v_mbcnt_lo_u32_b32 v78, s6, 0
	v_mbcnt_hi_u32_b32 v78, s7, v78
	v_lshl_add_u32 v78, v78, 2, s44
	ds_write2st64_b32 v78, v64, v76 offset1:16
	s_mov_b64 exec, -1
	s_add_u32 s24, s24, s8
	s_lshl2_add_u32 s42, s8, s42
	s_bcnt1_i32_b64 s9, s[6:7]
	s_add_u32 s39, s39, s9
	s_min_u32 s9, s39, 0xbc0
	s_lshl2_add_u32 s44, s9, s33
	v_ashrrev_i32_e32 v80, 31, v65
	v_or_b32_e32 v80, 0x80000000, v80
	v_xor_b32_e32 v65, v65, v80
	v_lshrrev_b32_e32 v80, 20, v65
	v_cmp_lt_u32_e64 s[10:11], s73, v80
	v_cmp_eq_u32_e64 s[14:15], s73, v80
	v_or_b32_e32 v81, 3, v79
	s_bcnt1_i32_b64 s8, s[10:11]
	v_mbcnt_lo_u32_b32 v82, s10, 0
	v_mbcnt_hi_u32_b32 v82, s11, v82
	v_lshl_add_u32 v82, v82, 2, s42
	s_mov_b64 exec, s[10:11]
	ds_write_b32 v82, v81 offset:16384
	s_mov_b64 exec, s[14:15]
	v_mbcnt_lo_u32_b32 v83, s14, 0
	v_mbcnt_hi_u32_b32 v83, s15, v83
	v_lshl_add_u32 v83, v83, 2, s44
	ds_write2st64_b32 v83, v65, v81 offset1:16
	s_mov_b64 exec, -1
	s_add_u32 s24, s24, s8
	s_lshl2_add_u32 s42, s8, s42
	s_bcnt1_i32_b64 s9, s[14:15]
	s_add_u32 s39, s39, s9
	s_min_u32 s9, s39, 0xbc0
	s_lshl2_add_u32 s44, s9, s33
	s_cmp_eq_u32 s1, 0
	s_cbranch_scc1 .Lsel2_done
	v_add_u32_e32 v79, 0x100, v73
	v_ashrrev_i32_e32 v75, 31, v58
	v_or_b32_e32 v75, 0x80000000, v75
	v_xor_b32_e32 v58, v58, v75
	v_lshrrev_b32_e32 v75, 20, v58
	v_cmp_lt_u32_e64 s[4:5], s73, v75
	v_cmp_eq_u32_e64 s[6:7], s73, v75
	s_bcnt1_i32_b64 s8, s[4:5]
	v_mbcnt_lo_u32_b32 v77, s4, 0
	v_mbcnt_hi_u32_b32 v77, s5, v77
	v_lshl_add_u32 v77, v77, 2, s42
	s_mov_b64 exec, s[4:5]
	ds_write_b32 v77, v79 offset:16384
	s_mov_b64 exec, s[6:7]
	v_mbcnt_lo_u32_b32 v78, s6, 0
	v_mbcnt_hi_u32_b32 v78, s7, v78
	v_lshl_add_u32 v78, v78, 2, s44
	ds_write2st64_b32 v78, v58, v79 offset1:16
	s_mov_b64 exec, -1
	s_add_u32 s24, s24, s8
	s_lshl2_add_u32 s42, s8, s42
	s_bcnt1_i32_b64 s9, s[6:7]
	s_add_u32 s39, s39, s9
	s_min_u32 s9, s39, 0xbc0
	s_lshl2_add_u32 s44, s9, s33
	v_ashrrev_i32_e32 v80, 31, v59
	v_or_b32_e32 v80, 0x80000000, v80
	v_xor_b32_e32 v59, v59, v80
	v_lshrrev_b32_e32 v80, 20, v59
	v_cmp_lt_u32_e64 s[10:11], s73, v80
	v_cmp_eq_u32_e64 s[14:15], s73, v80
	v_or_b32_e32 v81, 1, v79
	s_bcnt1_i32_b64 s8, s[10:11]
	v_mbcnt_lo_u32_b32 v82, s10, 0
	v_mbcnt_hi_u32_b32 v82, s11, v82
	v_lshl_add_u32 v82, v82, 2, s42
	s_mov_b64 exec, s[10:11]
	ds_write_b32 v82, v81 offset:16384
	s_mov_b64 exec, s[14:15]
	v_mbcnt_lo_u32_b32 v83, s14, 0
	v_mbcnt_hi_u32_b32 v83, s15, v83
	v_lshl_add_u32 v83, v83, 2, s44
	ds_write2st64_b32 v83, v59, v81 offset1:16
	s_mov_b64 exec, -1
	s_add_u32 s24, s24, s8
	s_lshl2_add_u32 s42, s8, s42
	s_bcnt1_i32_b64 s9, s[14:15]
	s_add_u32 s39, s39, s9
	s_min_u32 s9, s39, 0xbc0
	s_lshl2_add_u32 s44, s9, s33
	v_ashrrev_i32_e32 v75, 31, v60
	v_or_b32_e32 v75, 0x80000000, v75
	v_xor_b32_e32 v60, v60, v75
	v_lshrrev_b32_e32 v75, 20, v60
	v_cmp_lt_u32_e64 s[4:5], s73, v75
	v_cmp_eq_u32_e64 s[6:7], s73, v75
	v_or_b32_e32 v76, 2, v79
	s_bcnt1_i32_b64 s8, s[4:5]
	v_mbcnt_lo_u32_b32 v77, s4, 0
	v_mbcnt_hi_u32_b32 v77, s5, v77
	v_lshl_add_u32 v77, v77, 2, s42
	s_mov_b64 exec, s[4:5]
	ds_write_b32 v77, v76 offset:16384
	s_mov_b64 exec, s[6:7]
	v_mbcnt_lo_u32_b32 v78, s6, 0
	v_mbcnt_hi_u32_b32 v78, s7, v78
	v_lshl_add_u32 v78, v78, 2, s44
	ds_write2st64_b32 v78, v60, v76 offset1:16
	s_mov_b64 exec, -1
	s_add_u32 s24, s24, s8
	s_lshl2_add_u32 s42, s8, s42
	s_bcnt1_i32_b64 s9, s[6:7]
	s_add_u32 s39, s39, s9
	s_min_u32 s9, s39, 0xbc0
	s_lshl2_add_u32 s44, s9, s33
	v_ashrrev_i32_e32 v80, 31, v61
	v_or_b32_e32 v80, 0x80000000, v80
	v_xor_b32_e32 v61, v61, v80
	v_lshrrev_b32_e32 v80, 20, v61
	v_cmp_lt_u32_e64 s[10:11], s73, v80
	v_cmp_eq_u32_e64 s[14:15], s73, v80
	v_or_b32_e32 v81, 3, v79
	s_bcnt1_i32_b64 s8, s[10:11]
	v_mbcnt_lo_u32_b32 v82, s10, 0
	v_mbcnt_hi_u32_b32 v82, s11, v82
	v_lshl_add_u32 v82, v82, 2, s42
	s_mov_b64 exec, s[10:11]
	ds_write_b32 v82, v81 offset:16384
	s_mov_b64 exec, s[14:15]
	v_mbcnt_lo_u32_b32 v83, s14, 0
	v_mbcnt_hi_u32_b32 v83, s15, v83
	v_lshl_add_u32 v83, v83, 2, s44
	ds_write2st64_b32 v83, v61, v81 offset1:16
	s_mov_b64 exec, -1
	s_add_u32 s24, s24, s8
	s_lshl2_add_u32 s42, s8, s42
	s_bcnt1_i32_b64 s9, s[14:15]
	s_add_u32 s39, s39, s9
	s_min_u32 s9, s39, 0xbc0
	s_lshl2_add_u32 s44, s9, s33
	s_cmp_eq_u32 s1, 1
	s_cbranch_scc1 .Lsel2_done
; __device__ __forceinline__ unsigned f2key(float f) { const unsigned u = __float_as_uint(f); return (u & 0x80000000u) ? ~u : (u | 0x80000000u); }
; #define SEL_LOAD4(v_, i0_) do { _Pragma("unroll") for (int q = 0; q < 16; ++q) { const int i_ = (i0_) + 256 * q + 4 * lane; v_[q] = (i_ < n) ? srow4[i_ >> 2] : (f32x4){0.f, 0.f, 0.f, 0.f}; } } while (0)
; __device__ __forceinline__ void select256(LAS unsigned char* wl, const float* srow, int n, int lane) {
;     ...
;     for (int i0 = 0; i0 < n; i0 += 4096) {
;         f32x4 v[16]; SEL_LOAD4(v, i0);
; #pragma unroll
;         for (int q = 0; q < 16; ++q)
; #pragma unroll
;             for (int e = 0; e < 4; ++e) {
;                 const int i = i0 + 256 * q + 4 * lane + e; const bool in = i < n; const unsigned key = f2key(v[q][e]); const unsigned bin = key >> 20;
;                 const bool gt = in && bin > b1, eq = in && bin == b1;
;                 const unsigned long long bg = __ballot(gt), be = __ballot(eq);
;                 if (gt) { const unsigned pos = run + (unsigned)__popcll(bg & lt); if (pos < 256u) idx[pos] = i; }
;                 if (eq) { const unsigned pos = cc + (unsigned)__popcll(be & lt); if (pos < (unsigned)CAP) { candk[pos] = key; candi[pos] = i; } }
;                 run += (unsigned)__popcll(bg); cc += (unsigned)__popcll(be);
;             }
;     }
	v_add_u32_e32 v79, 0x200, v73
	v_ashrrev_i32_e32 v75, 31, v54
	v_or_b32_e32 v75, 0x80000000, v75
	v_xor_b32_e32 v54, v54, v75
	v_lshrrev_b32_e32 v75, 20, v54
	v_cmp_lt_u32_e64 s[4:5], s73, v75
	v_cmp_eq_u32_e64 s[6:7], s73, v75
	s_bcnt1_i32_b64 s8, s[4:5]
	v_mbcnt_lo_u32_b32 v77, s4, 0
	v_mbcnt_hi_u32_b32 v77, s5, v77
	v_lshl_add_u32 v77, v77, 2, s42
	s_mov_b64 exec, s[4:5]
	ds_write_b32 v77, v79 offset:16384
	s_mov_b64 exec, s[6:7]
	v_mbcnt_lo_u32_b32 v78, s6, 0
	v_mbcnt_hi_u32_b32 v78, s7, v78
	v_lshl_add_u32 v78, v78, 2, s44
	ds_write2st64_b32 v78, v54, v79 offset1:16
	s_mov_b64 exec, -1
	s_add_u32 s24, s24, s8
	s_lshl2_add_u32 s42, s8, s42
	s_bcnt1_i32_b64 s9, s[6:7]
	s_add_u32 s39, s39, s9
	s_min_u32 s9, s39, 0xbc0
	s_lshl2_add_u32 s44, s9, s33
	v_ashrrev_i32_e32 v80, 31, v55
	v_or_b32_e32 v80, 0x80000000, v80
	v_xor_b32_e32 v55, v55, v80
	v_lshrrev_b32_e32 v80, 20, v55
	v_cmp_lt_u32_e64 s[10:11], s73, v80
	v_cmp_eq_u32_e64 s[14:15], s73, v80
	v_or_b32_e32 v81, 1, v79
	s_bcnt1_i32_b64 s8, s[10:11]
	v_mbcnt_lo_u32_b32 v82, s10, 0
	v_mbcnt_hi_u32_b32 v82, s11, v82
	v_lshl_add_u32 v82, v82, 2, s42
	s_mov_b64 exec, s[10:11]
	ds_write_b32 v82, v81 offset:16384
	s_mov_b64 exec, s[14:15]
	v_mbcnt_lo_u32_b32 v83, s14, 0
	v_mbcnt_hi_u32_b32 v83, s15, v83
	v_lshl_add_u32 v83, v83, 2, s44
	ds_write2st64_b32 v83, v55, v81 offset1:16
	s_mov_b64 exec, -1
	s_add_u32 s24, s24, s8
	s_lshl2_add_u32 s42, s8, s42
	s_bcnt1_i32_b64 s9, s[14:15]
	s_add_u32 s39, s39, s9
	s_min_u32 s9, s39, 0xbc0
	s_lshl2_add_u32 s44, s9, s33
	v_ashrrev_i32_e32 v75, 31, v56
	v_or_b32_e32 v75, 0x80000000, v75
	v_xor_b32_e32 v56, v56, v75
	v_lshrrev_b32_e32 v75, 20, v56
	v_cmp_lt_u32_e64 s[4:5], s73, v75
	v_cmp_eq_u32_e64 s[6:7], s73, v75
	v_or_b32_e32 v76, 2, v79
	s_bcnt1_i32_b64 s8, s[4:5]
	v_mbcnt_lo_u32_b32 v77, s4, 0
	v_mbcnt_hi_u32_b32 v77, s5, v77
	v_lshl_add_u32 v77, v77, 2, s42
	s_mov_b64 exec, s[4:5]
	ds_write_b32 v77, v76 offset:16384
	s_mov_b64 exec, s[6:7]
	v_mbcnt_lo_u32_b32 v78, s6, 0
	v_mbcnt_hi_u32_b32 v78, s7, v78
	v_lshl_add_u32 v78, v78, 2, s44
	ds_write2st64_b32 v78, v56, v76 offset1:16
	s_mov_b64 exec, -1
	s_add_u32 s24, s24, s8
	s_lshl2_add_u32 s42, s8, s42
	s_bcnt1_i32_b64 s9, s[6:7]
	s_add_u32 s39, s39, s9
	s_min_u32 s9, s39, 0xbc0
	s_lshl2_add_u32 s44, s9, s33
	v_ashrrev_i32_e32 v80, 31, v57
	v_or_b32_e32 v80, 0x80000000, v80
	v_xor_b32_e32 v57, v57, v80
	v_lshrrev_b32_e32 v80, 20, v57
	v_cmp_lt_u32_e64 s[10:11], s73, v80
	v_cmp_eq_u32_e64 s[14:15], s73, v80
	v_or_b32_e32 v81, 3, v79
	s_bcnt1_i32_b64 s8, s[10:11]
	v_mbcnt_lo_u32_b32 v82, s10, 0
	v_mbcnt_hi_u32_b32 v82, s11, v82
	v_lshl_add_u32 v82, v82, 2, s42
	s_mov_b64 exec, s[10:11]
	ds_write_b32 v82, v81 offset:16384
	s_mov_b64 exec, s[14:15]
	v_mbcnt_lo_u32_b32 v83, s14, 0
	v_mbcnt_hi_u32_b32 v83, s15, v83
	v_lshl_add_u32 v83, v83, 2, s44
	ds_write2st64_b32 v83, v57, v81 offset1:16
	s_mov_b64 exec, -1
	s_add_u32 s24, s24, s8
	s_lshl2_add_u32 s42, s8, s42
	s_bcnt1_i32_b64 s9, s[14:15]
	s_add_u32 s39, s39, s9
	s_min_u32 s9, s39, 0xbc0
	s_lshl2_add_u32 s44, s9, s33
	s_cmp_eq_u32 s1, 2
	s_cbranch_scc1 .Lsel2_done
	v_add_u32_e32 v79, 0x300, v73
	v_ashrrev_i32_e32 v75, 31, v50
	v_or_b32_e32 v75, 0x80000000, v75
	v_xor_b32_e32 v50, v50, v75
	v_lshrrev_b32_e32 v75, 20, v50
	v_cmp_lt_u32_e64 s[4:5], s73, v75
	v_cmp_eq_u32_e64 s[6:7], s73, v75
	s_bcnt1_i32_b64 s8, s[4:5]
	v_mbcnt_lo_u32_b32 v77, s4, 0
	v_mbcnt_hi_u32_b32 v77, s5, v77
	v_lshl_add_u32 v77, v77, 2, s42
	s_mov_b64 exec, s[4:5]
	ds_write_b32 v77, v79 offset:16384
	s_mov_b64 exec, s[6:7]
	v_mbcnt_lo_u32_b32 v78, s6, 0
	v_mbcnt_hi_u32_b32 v78, s7, v78
	v_lshl_add_u32 v78, v78, 2, s44
	ds_write2st64_b32 v78, v50, v79 offset1:16
	s_mov_b64 exec, -1
	s_add_u32 s24, s24, s8
	s_lshl2_add_u32 s42, s8, s42
	s_bcnt1_i32_b64 s9, s[6:7]
	s_add_u32 s39, s39, s9
	s_min_u32 s9, s39, 0xbc0
	s_lshl2_add_u32 s44, s9, s33
	v_ashrrev_i32_e32 v80, 31, v51
	v_or_b32_e32 v80, 0x80000000, v80
	v_xor_b32_e32 v51, v51, v80
	v_lshrrev_b32_e32 v80, 20, v51
	v_cmp_lt_u32_e64 s[10:11], s73, v80
	v_cmp_eq_u32_e64 s[14:15], s73, v80
	v_or_b32_e32 v81, 1, v79
	s_bcnt1_i32_b64 s8, s[10:11]
	v_mbcnt_lo_u32_b32 v82, s10, 0
	v_mbcnt_hi_u32_b32 v82, s11, v82
	v_lshl_add_u32 v82, v82, 2, s42
	s_mov_b64 exec, s[10:11]
	ds_write_b32 v82, v81 offset:16384
	s_mov_b64 exec, s[14:15]
	v_mbcnt_lo_u32_b32 v83, s14, 0
	v_mbcnt_hi_u32_b32 v83, s15, v83
	v_lshl_add_u32 v83, v83, 2, s44
	ds_write2st64_b32 v83, v51, v81 offset1:16
	s_mov_b64 exec, -1
	s_add_u32 s24, s24, s8
	s_lshl2_add_u32 s42, s8, s42
	s_bcnt1_i32_b64 s9, s[14:15]
	s_add_u32 s39, s39, s9
	s_min_u32 s9, s39, 0xbc0
	s_lshl2_add_u32 s44, s9, s33
	v_ashrrev_i32_e32 v75, 31, v52
	v_or_b32_e32 v75, 0x80000000, v75
	v_xor_b32_e32 v52, v52, v75
	v_lshrrev_b32_e32 v75, 20, v52
	v_cmp_lt_u32_e64 s[4:5], s73, v75
	v_cmp_eq_u32_e64 s[6:7], s73, v75
	v_or_b32_e32 v76, 2, v79
	s_bcnt1_i32_b64 s8, s[4:5]
	v_mbcnt_lo_u32_b32 v77, s4, 0
	v_mbcnt_hi_u32_b32 v77, s5, v77
	v_lshl_add_u32 v77, v77, 2, s42
	s_mov_b64 exec, s[4:5]
	ds_write_b32 v77, v76 offset:16384
	s_mov_b64 exec, s[6:7]
	v_mbcnt_lo_u32_b32 v78, s6, 0
	v_mbcnt_hi_u32_b32 v78, s7, v78
	v_lshl_add_u32 v78, v78, 2, s44
	ds_write2st64_b32 v78, v52, v76 offset1:16
	s_mov_b64 exec, -1
	s_add_u32 s24, s24, s8
	s_lshl2_add_u32 s42, s8, s42
	s_bcnt1_i32_b64 s9, s[6:7]
	s_add_u32 s39, s39, s9
	s_min_u32 s9, s39, 0xbc0
	s_lshl2_add_u32 s44, s9, s33
	v_ashrrev_i32_e32 v80, 31, v53
	v_or_b32_e32 v80, 0x80000000, v80
	v_xor_b32_e32 v53, v53, v80
	v_lshrrev_b32_e32 v80, 20, v53
	v_cmp_lt_u32_e64 s[10:11], s73, v80
	v_cmp_eq_u32_e64 s[14:15], s73, v80
	v_or_b32_e32 v81, 3, v79
	s_bcnt1_i32_b64 s8, s[10:11]
	v_mbcnt_lo_u32_b32 v82, s10, 0
	v_mbcnt_hi_u32_b32 v82, s11, v82
	v_lshl_add_u32 v82, v82, 2, s42
	s_mov_b64 exec, s[10:11]
	ds_write_b32 v82, v81 offset:16384
	s_mov_b64 exec, s[14:15]
	v_mbcnt_lo_u32_b32 v83, s14, 0
	v_mbcnt_hi_u32_b32 v83, s15, v83
	v_lshl_add_u32 v83, v83, 2, s44
	ds_write2st64_b32 v83, v53, v81 offset1:16
	s_mov_b64 exec, -1
	s_add_u32 s24, s24, s8
	s_lshl2_add_u32 s42, s8, s42
	s_bcnt1_i32_b64 s9, s[14:15]
	s_add_u32 s39, s39, s9
	s_min_u32 s9, s39, 0xbc0
	s_lshl2_add_u32 s44, s9, s33
	s_cmp_eq_u32 s1, 3
	s_cbranch_scc1 .Lsel2_done
; __device__ __forceinline__ unsigned f2key(float f) { const unsigned u = __float_as_uint(f); return (u & 0x80000000u) ? ~u : (u | 0x80000000u); }
; #define MK_HADD(p) __hip_atomic_fetch_add((p), 1u, __ATOMIC_RELAXED, __HIP_MEMORY_SCOPE_WORKGROUP)
; #define SEL_LOAD4(v_, i0_) do { _Pragma("unroll") for (int q = 0; q < 16; ++q) { const int i_ = (i0_) + 256 * q + 4 * lane; v_[q] = (i_ < n) ? srow4[i_ >> 2] : (f32x4){0.f, 0.f, 0.f, 0.f}; } } while (0)
; __device__ __forceinline__ void select256(LAS unsigned char* wl, const float* srow, int n, int lane) {
;     ...
;     for (int i0 = 0; i0 < n; i0 += 4096) {
;         f32x4 v[16]; SEL_LOAD4(v, i0);
; #pragma unroll
;         for (int q = 0; q < 16; ++q)
; #pragma unroll
;             for (int e = 0; e < 4; ++e) {
;                 const int i = i0 + 256 * q + 4 * lane + e; const bool in = i < n; const unsigned key = f2key(v[q][e]); const unsigned bin = key >> 20;
;                 const bool gt = in && bin > b1, eq = in && bin == b1;
;                 const unsigned long long bg = __ballot(gt), be = __ballot(eq);
;                 if (gt) { const unsigned pos = run + (unsigned)__popcll(bg & lt); if (pos < 256u) idx[pos] = i; }
;                 if (eq) { const unsigned pos = cc + (unsigned)__popcll(be & lt); if (pos < (unsigned)CAP) { candk[pos] = key; candi[pos] = i; } }
;                 run += (unsigned)__popcll(bg); cc += (unsigned)__popcll(be);
;             }
;     }
;     ...
;     if (cc <= (unsigned)CAP) {
;         hist_zero<1024>(hist2, lane);
;         for (unsigned c = lane; c < cc; c += 64) MK_HADD(hist2 + ((candk[c] >> 10) & 1023u));
;         const unsigned b2 = find_bin<10>(hist2, k, lane);
;         hist_zero<1024>(hist2, lane);
	v_add_u32_e32 v79, 0x400, v73
	v_ashrrev_i32_e32 v75, 31, v46
	v_or_b32_e32 v75, 0x80000000, v75
	v_xor_b32_e32 v46, v46, v75
	v_lshrrev_b32_e32 v75, 20, v46
	v_cmp_lt_u32_e64 s[4:5], s73, v75
	v_cmp_eq_u32_e64 s[6:7], s73, v75
	s_bcnt1_i32_b64 s8, s[4:5]
	v_mbcnt_lo_u32_b32 v77, s4, 0
	v_mbcnt_hi_u32_b32 v77, s5, v77
	v_lshl_add_u32 v77, v77, 2, s42
	s_mov_b64 exec, s[4:5]
	ds_write_b32 v77, v79 offset:16384
	s_mov_b64 exec, s[6:7]
	v_mbcnt_lo_u32_b32 v78, s6, 0
	v_mbcnt_hi_u32_b32 v78, s7, v78
	v_lshl_add_u32 v78, v78, 2, s44
	ds_write2st64_b32 v78, v46, v79 offset1:16
	s_mov_b64 exec, -1
	s_add_u32 s24, s24, s8
	s_lshl2_add_u32 s42, s8, s42
	s_bcnt1_i32_b64 s9, s[6:7]
	s_add_u32 s39, s39, s9
	s_min_u32 s9, s39, 0xbc0
	s_lshl2_add_u32 s44, s9, s33
	v_ashrrev_i32_e32 v80, 31, v47
	v_or_b32_e32 v80, 0x80000000, v80
	v_xor_b32_e32 v47, v47, v80
	v_lshrrev_b32_e32 v80, 20, v47
	v_cmp_lt_u32_e64 s[10:11], s73, v80
	v_cmp_eq_u32_e64 s[14:15], s73, v80
	v_or_b32_e32 v81, 1, v79
	s_bcnt1_i32_b64 s8, s[10:11]
	v_mbcnt_lo_u32_b32 v82, s10, 0
	v_mbcnt_hi_u32_b32 v82, s11, v82
	v_lshl_add_u32 v82, v82, 2, s42
	s_mov_b64 exec, s[10:11]
	ds_write_b32 v82, v81 offset:16384
	s_mov_b64 exec, s[14:15]
	v_mbcnt_lo_u32_b32 v83, s14, 0
	v_mbcnt_hi_u32_b32 v83, s15, v83
	v_lshl_add_u32 v83, v83, 2, s44
	ds_write2st64_b32 v83, v47, v81 offset1:16
	s_mov_b64 exec, -1
	s_add_u32 s24, s24, s8
	s_lshl2_add_u32 s42, s8, s42
	s_bcnt1_i32_b64 s9, s[14:15]
	s_add_u32 s39, s39, s9
	s_min_u32 s9, s39, 0xbc0
	s_lshl2_add_u32 s44, s9, s33
	v_ashrrev_i32_e32 v75, 31, v48
	v_or_b32_e32 v75, 0x80000000, v75
	v_xor_b32_e32 v48, v48, v75
	v_lshrrev_b32_e32 v75, 20, v48
	v_cmp_lt_u32_e64 s[4:5], s73, v75
	v_cmp_eq_u32_e64 s[6:7], s73, v75
	v_or_b32_e32 v76, 2, v79
	s_bcnt1_i32_b64 s8, s[4:5]
	v_mbcnt_lo_u32_b32 v77, s4, 0
	v_mbcnt_hi_u32_b32 v77, s5, v77
	v_lshl_add_u32 v77, v77, 2, s42
	s_mov_b64 exec, s[4:5]
	ds_write_b32 v77, v76 offset:16384
	s_mov_b64 exec, s[6:7]
	v_mbcnt_lo_u32_b32 v78, s6, 0
	v_mbcnt_hi_u32_b32 v78, s7, v78
	v_lshl_add_u32 v78, v78, 2, s44
	ds_write2st64_b32 v78, v48, v76 offset1:16
	s_mov_b64 exec, -1
	s_add_u32 s24, s24, s8
	s_lshl2_add_u32 s42, s8, s42
	s_bcnt1_i32_b64 s9, s[6:7]
	s_add_u32 s39, s39, s9
	s_min_u32 s9, s39, 0xbc0
	s_lshl2_add_u32 s44, s9, s33
	v_ashrrev_i32_e32 v80, 31, v49
	v_or_b32_e32 v80, 0x80000000, v80
	v_xor_b32_e32 v49, v49, v80
	v_lshrrev_b32_e32 v80, 20, v49
	v_cmp_lt_u32_e64 s[10:11], s73, v80
	v_cmp_eq_u32_e64 s[14:15], s73, v80
	v_or_b32_e32 v81, 3, v79
	s_bcnt1_i32_b64 s8, s[10:11]
	v_mbcnt_lo_u32_b32 v82, s10, 0
	v_mbcnt_hi_u32_b32 v82, s11, v82
	v_lshl_add_u32 v82, v82, 2, s42
	s_mov_b64 exec, s[10:11]
	ds_write_b32 v82, v81 offset:16384
	s_mov_b64 exec, s[14:15]
	v_mbcnt_lo_u32_b32 v83, s14, 0
	v_mbcnt_hi_u32_b32 v83, s15, v83
	v_lshl_add_u32 v83, v83, 2, s44
	ds_write2st64_b32 v83, v49, v81 offset1:16
	s_mov_b64 exec, -1
	s_add_u32 s24, s24, s8
	s_lshl2_add_u32 s42, s8, s42
	s_bcnt1_i32_b64 s9, s[14:15]
	s_add_u32 s39, s39, s9
	s_min_u32 s9, s39, 0xbc0
	s_lshl2_add_u32 s44, s9, s33
	s_cmp_eq_u32 s1, 4
	s_cbranch_scc1 .Lsel2_done
	v_add_u32_e32 v79, 0x500, v73
	v_ashrrev_i32_e32 v75, 31, v42
	v_or_b32_e32 v75, 0x80000000, v75
	v_xor_b32_e32 v42, v42, v75
	v_lshrrev_b32_e32 v75, 20, v42
	v_cmp_lt_u32_e64 s[4:5], s73, v75
	v_cmp_eq_u32_e64 s[6:7], s73, v75
	s_bcnt1_i32_b64 s8, s[4:5]
	v_mbcnt_lo_u32_b32 v77, s4, 0
	v_mbcnt_hi_u32_b32 v77, s5, v77
	v_lshl_add_u32 v77, v77, 2, s42
	s_mov_b64 exec, s[4:5]
	ds_write_b32 v77, v79 offset:16384
	s_mov_b64 exec, s[6:7]
	v_mbcnt_lo_u32_b32 v78, s6, 0
	v_mbcnt_hi_u32_b32 v78, s7, v78
	v_lshl_add_u32 v78, v78, 2, s44
	ds_write2st64_b32 v78, v42, v79 offset1:16
	s_mov_b64 exec, -1
	s_add_u32 s24, s24, s8
	s_lshl2_add_u32 s42, s8, s42
	s_bcnt1_i32_b64 s9, s[6:7]
	s_add_u32 s39, s39, s9
	s_min_u32 s9, s39, 0xbc0
	s_lshl2_add_u32 s44, s9, s33
	v_ashrrev_i32_e32 v80, 31, v43
	v_or_b32_e32 v80, 0x80000000, v80
	v_xor_b32_e32 v43, v43, v80
	v_lshrrev_b32_e32 v80, 20, v43
	v_cmp_lt_u32_e64 s[10:11], s73, v80
	v_cmp_eq_u32_e64 s[14:15], s73, v80
	v_or_b32_e32 v81, 1, v79
	s_bcnt1_i32_b64 s8, s[10:11]
	v_mbcnt_lo_u32_b32 v82, s10, 0
	v_mbcnt_hi_u32_b32 v82, s11, v82
	v_lshl_add_u32 v82, v82, 2, s42
	s_mov_b64 exec, s[10:11]
	ds_write_b32 v82, v81 offset:16384
	s_mov_b64 exec, s[14:15]
	v_mbcnt_lo_u32_b32 v83, s14, 0
	v_mbcnt_hi_u32_b32 v83, s15, v83
	v_lshl_add_u32 v83, v83, 2, s44
	ds_write2st64_b32 v83, v43, v81 offset1:16
	s_mov_b64 exec, -1
	s_add_u32 s24, s24, s8
	s_lshl2_add_u32 s42, s8, s42
	s_bcnt1_i32_b64 s9, s[14:15]
	s_add_u32 s39, s39, s9
	s_min_u32 s9, s39, 0xbc0
	s_lshl2_add_u32 s44, s9, s33
	v_ashrrev_i32_e32 v75, 31, v44
	v_or_b32_e32 v75, 0x80000000, v75
	v_xor_b32_e32 v44, v44, v75
	v_lshrrev_b32_e32 v75, 20, v44
	v_cmp_lt_u32_e64 s[4:5], s73, v75
	v_cmp_eq_u32_e64 s[6:7], s73, v75
	v_or_b32_e32 v76, 2, v79
	s_bcnt1_i32_b64 s8, s[4:5]
	v_mbcnt_lo_u32_b32 v77, s4, 0
	v_mbcnt_hi_u32_b32 v77, s5, v77
	v_lshl_add_u32 v77, v77, 2, s42
	s_mov_b64 exec, s[4:5]
	ds_write_b32 v77, v76 offset:16384
	s_mov_b64 exec, s[6:7]
	v_mbcnt_lo_u32_b32 v78, s6, 0
	v_mbcnt_hi_u32_b32 v78, s7, v78
	v_lshl_add_u32 v78, v78, 2, s44
	ds_write2st64_b32 v78, v44, v76 offset1:16
	s_mov_b64 exec, -1
	s_add_u32 s24, s24, s8
	s_lshl2_add_u32 s42, s8, s42
	s_bcnt1_i32_b64 s9, s[6:7]
	s_add_u32 s39, s39, s9
	s_min_u32 s9, s39, 0xbc0
	s_lshl2_add_u32 s44, s9, s33
	v_ashrrev_i32_e32 v80, 31, v45
	v_or_b32_e32 v80, 0x80000000, v80
	v_xor_b32_e32 v45, v45, v80
	v_lshrrev_b32_e32 v80, 20, v45
	v_cmp_lt_u32_e64 s[10:11], s73, v80
	v_cmp_eq_u32_e64 s[14:15], s73, v80
	v_or_b32_e32 v81, 3, v79
	s_bcnt1_i32_b64 s8, s[10:11]
	v_mbcnt_lo_u32_b32 v82, s10, 0
	v_mbcnt_hi_u32_b32 v82, s11, v82
	v_lshl_add_u32 v82, v82, 2, s42
	s_mov_b64 exec, s[10:11]
	ds_write_b32 v82, v81 offset:16384
	s_mov_b64 exec, s[14:15]
	v_mbcnt_lo_u32_b32 v83, s14, 0
	v_mbcnt_hi_u32_b32 v83, s15, v83
	v_lshl_add_u32 v83, v83, 2, s44
	ds_write2st64_b32 v83, v45, v81 offset1:16
	s_mov_b64 exec, -1
	s_add_u32 s24, s24, s8
	s_lshl2_add_u32 s42, s8, s42
	s_bcnt1_i32_b64 s9, s[14:15]
	s_add_u32 s39, s39, s9
	s_min_u32 s9, s39, 0xbc0
	s_lshl2_add_u32 s44, s9, s33
	s_cmp_eq_u32 s1, 5
	s_cbranch_scc1 .Lsel2_done
; __device__ __forceinline__ unsigned f2key(float f) { const unsigned u = __float_as_uint(f); return (u & 0x80000000u) ? ~u : (u | 0x80000000u); }
; #define SEL_LOAD4(v_, i0_) do { _Pragma("unroll") for (int q = 0; q < 16; ++q) { const int i_ = (i0_) + 256 * q + 4 * lane; v_[q] = (i_ < n) ? srow4[i_ >> 2] : (f32x4){0.f, 0.f, 0.f, 0.f}; } } while (0)
; __device__ __forceinline__ void select256(LAS unsigned char* wl, const float* srow, int n, int lane) {
;     ...
;     for (int i0 = 0; i0 < n; i0 += 4096) {
;         f32x4 v[16]; SEL_LOAD4(v, i0);
; #pragma unroll
;         for (int q = 0; q < 16; ++q)
; #pragma unroll
;             for (int e = 0; e < 4; ++e) {
;                 const int i = i0 + 256 * q + 4 * lane + e; const bool in = i < n; const unsigned key = f2key(v[q][e]); const unsigned bin = key >> 20;
;                 const bool gt = in && bin > b1, eq = in && bin == b1;
;                 const unsigned long long bg = __ballot(gt), be = __ballot(eq);
;                 if (gt) { const unsigned pos = run + (unsigned)__popcll(bg & lt); if (pos < 256u) idx[pos] = i; }
;                 if (eq) { const unsigned pos = cc + (unsigned)__popcll(be & lt); if (pos < (unsigned)CAP) { candk[pos] = key; candi[pos] = i; } }
;                 run += (unsigned)__popcll(bg); cc += (unsigned)__popcll(be);
;             }
;     }
	v_add_u32_e32 v79, 0x600, v73
	v_ashrrev_i32_e32 v75, 31, v38
	v_or_b32_e32 v75, 0x80000000, v75
	v_xor_b32_e32 v38, v38, v75
	v_lshrrev_b32_e32 v75, 20, v38
	v_cmp_lt_u32_e64 s[4:5], s73, v75
	v_cmp_eq_u32_e64 s[6:7], s73, v75
	s_bcnt1_i32_b64 s8, s[4:5]
	v_mbcnt_lo_u32_b32 v77, s4, 0
	v_mbcnt_hi_u32_b32 v77, s5, v77
	v_lshl_add_u32 v77, v77, 2, s42
	s_mov_b64 exec, s[4:5]
	ds_write_b32 v77, v79 offset:16384
	s_mov_b64 exec, s[6:7]
	v_mbcnt_lo_u32_b32 v78, s6, 0
	v_mbcnt_hi_u32_b32 v78, s7, v78
	v_lshl_add_u32 v78, v78, 2, s44
	ds_write2st64_b32 v78, v38, v79 offset1:16
	s_mov_b64 exec, -1
	s_add_u32 s24, s24, s8
	s_lshl2_add_u32 s42, s8, s42
	s_bcnt1_i32_b64 s9, s[6:7]
	s_add_u32 s39, s39, s9
	s_min_u32 s9, s39, 0xbc0
	s_lshl2_add_u32 s44, s9, s33
	v_ashrrev_i32_e32 v80, 31, v39
	v_or_b32_e32 v80, 0x80000000, v80
	v_xor_b32_e32 v39, v39, v80
	v_lshrrev_b32_e32 v80, 20, v39
	v_cmp_lt_u32_e64 s[10:11], s73, v80
	v_cmp_eq_u32_e64 s[14:15], s73, v80
	v_or_b32_e32 v81, 1, v79
	s_bcnt1_i32_b64 s8, s[10:11]
	v_mbcnt_lo_u32_b32 v82, s10, 0
	v_mbcnt_hi_u32_b32 v82, s11, v82
	v_lshl_add_u32 v82, v82, 2, s42
	s_mov_b64 exec, s[10:11]
	ds_write_b32 v82, v81 offset:16384
	s_mov_b64 exec, s[14:15]
	v_mbcnt_lo_u32_b32 v83, s14, 0
	v_mbcnt_hi_u32_b32 v83, s15, v83
	v_lshl_add_u32 v83, v83, 2, s44
	ds_write2st64_b32 v83, v39, v81 offset1:16
	s_mov_b64 exec, -1
	s_add_u32 s24, s24, s8
	s_lshl2_add_u32 s42, s8, s42
	s_bcnt1_i32_b64 s9, s[14:15]
	s_add_u32 s39, s39, s9
	s_min_u32 s9, s39, 0xbc0
	s_lshl2_add_u32 s44, s9, s33
	v_ashrrev_i32_e32 v75, 31, v40
	v_or_b32_e32 v75, 0x80000000, v75
	v_xor_b32_e32 v40, v40, v75
	v_lshrrev_b32_e32 v75, 20, v40
	v_cmp_lt_u32_e64 s[4:5], s73, v75
	v_cmp_eq_u32_e64 s[6:7], s73, v75
	v_or_b32_e32 v76, 2, v79
	s_bcnt1_i32_b64 s8, s[4:5]
	v_mbcnt_lo_u32_b32 v77, s4, 0
	v_mbcnt_hi_u32_b32 v77, s5, v77
	v_lshl_add_u32 v77, v77, 2, s42
	s_mov_b64 exec, s[4:5]
	ds_write_b32 v77, v76 offset:16384
	s_mov_b64 exec, s[6:7]
	v_mbcnt_lo_u32_b32 v78, s6, 0
	v_mbcnt_hi_u32_b32 v78, s7, v78
	v_lshl_add_u32 v78, v78, 2, s44
	ds_write2st64_b32 v78, v40, v76 offset1:16
	s_mov_b64 exec, -1
	s_add_u32 s24, s24, s8
	s_lshl2_add_u32 s42, s8, s42
	s_bcnt1_i32_b64 s9, s[6:7]
	s_add_u32 s39, s39, s9
	s_min_u32 s9, s39, 0xbc0
	s_lshl2_add_u32 s44, s9, s33
	v_ashrrev_i32_e32 v80, 31, v41
	v_or_b32_e32 v80, 0x80000000, v80
	v_xor_b32_e32 v41, v41, v80
	v_lshrrev_b32_e32 v80, 20, v41
	v_cmp_lt_u32_e64 s[10:11], s73, v80
	v_cmp_eq_u32_e64 s[14:15], s73, v80
	v_or_b32_e32 v81, 3, v79
	s_bcnt1_i32_b64 s8, s[10:11]
	v_mbcnt_lo_u32_b32 v82, s10, 0
	v_mbcnt_hi_u32_b32 v82, s11, v82
	v_lshl_add_u32 v82, v82, 2, s42
	s_mov_b64 exec, s[10:11]
	ds_write_b32 v82, v81 offset:16384
	s_mov_b64 exec, s[14:15]
	v_mbcnt_lo_u32_b32 v83, s14, 0
	v_mbcnt_hi_u32_b32 v83, s15, v83
	v_lshl_add_u32 v83, v83, 2, s44
	ds_write2st64_b32 v83, v41, v81 offset1:16
	s_mov_b64 exec, -1
	s_add_u32 s24, s24, s8
	s_lshl2_add_u32 s42, s8, s42
	s_bcnt1_i32_b64 s9, s[14:15]
	s_add_u32 s39, s39, s9
	s_min_u32 s9, s39, 0xbc0
	s_lshl2_add_u32 s44, s9, s33
	s_cmp_eq_u32 s1, 6
	s_cbranch_scc1 .Lsel2_done
	v_add_u32_e32 v79, 0x700, v73
	v_ashrrev_i32_e32 v75, 31, v34
	v_or_b32_e32 v75, 0x80000000, v75
	v_xor_b32_e32 v34, v34, v75
	v_lshrrev_b32_e32 v75, 20, v34
	v_cmp_lt_u32_e64 s[4:5], s73, v75
	v_cmp_eq_u32_e64 s[6:7], s73, v75
	s_bcnt1_i32_b64 s8, s[4:5]
	v_mbcnt_lo_u32_b32 v77, s4, 0
	v_mbcnt_hi_u32_b32 v77, s5, v77
	v_lshl_add_u32 v77, v77, 2, s42
	s_mov_b64 exec, s[4:5]
	ds_write_b32 v77, v79 offset:16384
	s_mov_b64 exec, s[6:7]
	v_mbcnt_lo_u32_b32 v78, s6, 0
	v_mbcnt_hi_u32_b32 v78, s7, v78
	v_lshl_add_u32 v78, v78, 2, s44
	ds_write2st64_b32 v78, v34, v79 offset1:16
	s_mov_b64 exec, -1
	s_add_u32 s24, s24, s8
	s_lshl2_add_u32 s42, s8, s42
	s_bcnt1_i32_b64 s9, s[6:7]
	s_add_u32 s39, s39, s9
	s_min_u32 s9, s39, 0xbc0
	s_lshl2_add_u32 s44, s9, s33
	v_ashrrev_i32_e32 v80, 31, v35
	v_or_b32_e32 v80, 0x80000000, v80
	v_xor_b32_e32 v35, v35, v80
	v_lshrrev_b32_e32 v80, 20, v35
	v_cmp_lt_u32_e64 s[10:11], s73, v80
	v_cmp_eq_u32_e64 s[14:15], s73, v80
	v_or_b32_e32 v81, 1, v79
	s_bcnt1_i32_b64 s8, s[10:11]
	v_mbcnt_lo_u32_b32 v82, s10, 0
	v_mbcnt_hi_u32_b32 v82, s11, v82
	v_lshl_add_u32 v82, v82, 2, s42
	s_mov_b64 exec, s[10:11]
	ds_write_b32 v82, v81 offset:16384
	s_mov_b64 exec, s[14:15]
	v_mbcnt_lo_u32_b32 v83, s14, 0
	v_mbcnt_hi_u32_b32 v83, s15, v83
	v_lshl_add_u32 v83, v83, 2, s44
	ds_write2st64_b32 v83, v35, v81 offset1:16
	s_mov_b64 exec, -1
	s_add_u32 s24, s24, s8
	s_lshl2_add_u32 s42, s8, s42
	s_bcnt1_i32_b64 s9, s[14:15]
	s_add_u32 s39, s39, s9
	s_min_u32 s9, s39, 0xbc0
	s_lshl2_add_u32 s44, s9, s33
	v_ashrrev_i32_e32 v75, 31, v36
	v_or_b32_e32 v75, 0x80000000, v75
	v_xor_b32_e32 v36, v36, v75
	v_lshrrev_b32_e32 v75, 20, v36
	v_cmp_lt_u32_e64 s[4:5], s73, v75
	v_cmp_eq_u32_e64 s[6:7], s73, v75
	v_or_b32_e32 v76, 2, v79
	s_bcnt1_i32_b64 s8, s[4:5]
	v_mbcnt_lo_u32_b32 v77, s4, 0
	v_mbcnt_hi_u32_b32 v77, s5, v77
	v_lshl_add_u32 v77, v77, 2, s42
	s_mov_b64 exec, s[4:5]
	ds_write_b32 v77, v76 offset:16384
	s_mov_b64 exec, s[6:7]
	v_mbcnt_lo_u32_b32 v78, s6, 0
	v_mbcnt_hi_u32_b32 v78, s7, v78
	v_lshl_add_u32 v78, v78, 2, s44
	ds_write2st64_b32 v78, v36, v76 offset1:16
	s_mov_b64 exec, -1
	s_add_u32 s24, s24, s8
	s_lshl2_add_u32 s42, s8, s42
	s_bcnt1_i32_b64 s9, s[6:7]
	s_add_u32 s39, s39, s9
	s_min_u32 s9, s39, 0xbc0
	s_lshl2_add_u32 s44, s9, s33
	v_ashrrev_i32_e32 v80, 31, v37
	v_or_b32_e32 v80, 0x80000000, v80
	v_xor_b32_e32 v37, v37, v80
	v_lshrrev_b32_e32 v80, 20, v37
	v_cmp_lt_u32_e64 s[10:11], s73, v80
	v_cmp_eq_u32_e64 s[14:15], s73, v80
	v_or_b32_e32 v81, 3, v79
	s_bcnt1_i32_b64 s8, s[10:11]
	v_mbcnt_lo_u32_b32 v82, s10, 0
	v_mbcnt_hi_u32_b32 v82, s11, v82
	v_lshl_add_u32 v82, v82, 2, s42
	s_mov_b64 exec, s[10:11]
	ds_write_b32 v82, v81 offset:16384
	s_mov_b64 exec, s[14:15]
	v_mbcnt_lo_u32_b32 v83, s14, 0
	v_mbcnt_hi_u32_b32 v83, s15, v83
	v_lshl_add_u32 v83, v83, 2, s44
	ds_write2st64_b32 v83, v37, v81 offset1:16
	s_mov_b64 exec, -1
	s_add_u32 s24, s24, s8
	s_lshl2_add_u32 s42, s8, s42
	s_bcnt1_i32_b64 s9, s[14:15]
	s_add_u32 s39, s39, s9
	s_min_u32 s9, s39, 0xbc0
	s_lshl2_add_u32 s44, s9, s33
	s_cmp_eq_u32 s1, 7
	s_cbranch_scc1 .Lsel2_done
; __device__ __forceinline__ unsigned f2key(float f) { const unsigned u = __float_as_uint(f); return (u & 0x80000000u) ? ~u : (u | 0x80000000u); }
; #define SEL_LOAD4(v_, i0_) do { _Pragma("unroll") for (int q = 0; q < 16; ++q) { const int i_ = (i0_) + 256 * q + 4 * lane; v_[q] = (i_ < n) ? srow4[i_ >> 2] : (f32x4){0.f, 0.f, 0.f, 0.f}; } } while (0)
; __device__ __forceinline__ void select256(LAS unsigned char* wl, const float* srow, int n, int lane) {
;     ...
;     for (int i0 = 0; i0 < n; i0 += 4096) {
;         f32x4 v[16]; SEL_LOAD4(v, i0);
; #pragma unroll
;         for (int q = 0; q < 16; ++q)
; #pragma unroll
;             for (int e = 0; e < 4; ++e) {
;                 const int i = i0 + 256 * q + 4 * lane + e; const bool in = i < n; const unsigned key = f2key(v[q][e]); const unsigned bin = key >> 20;
;                 const bool gt = in && bin > b1, eq = in && bin == b1;
;                 const unsigned long long bg = __ballot(gt), be = __ballot(eq);
;                 if (gt) { const unsigned pos = run + (unsigned)__popcll(bg & lt); if (pos < 256u) idx[pos] = i; }
;                 if (eq) { const unsigned pos = cc + (unsigned)__popcll(be & lt); if (pos < (unsigned)CAP) { candk[pos] = key; candi[pos] = i; } }
;                 run += (unsigned)__popcll(bg); cc += (unsigned)__popcll(be);
;             }
;     }
	v_add_u32_e32 v79, 0x800, v73
	v_ashrrev_i32_e32 v75, 31, v30
	v_or_b32_e32 v75, 0x80000000, v75
	v_xor_b32_e32 v30, v30, v75
	v_lshrrev_b32_e32 v75, 20, v30
	v_cmp_lt_u32_e64 s[4:5], s73, v75
	v_cmp_eq_u32_e64 s[6:7], s73, v75
	s_bcnt1_i32_b64 s8, s[4:5]
	v_mbcnt_lo_u32_b32 v77, s4, 0
	v_mbcnt_hi_u32_b32 v77, s5, v77
	v_lshl_add_u32 v77, v77, 2, s42
	s_mov_b64 exec, s[4:5]
	ds_write_b32 v77, v79 offset:16384
	s_mov_b64 exec, s[6:7]
	v_mbcnt_lo_u32_b32 v78, s6, 0
	v_mbcnt_hi_u32_b32 v78, s7, v78
	v_lshl_add_u32 v78, v78, 2, s44
	ds_write2st64_b32 v78, v30, v79 offset1:16
	s_mov_b64 exec, -1
	s_add_u32 s24, s24, s8
	s_lshl2_add_u32 s42, s8, s42
	s_bcnt1_i32_b64 s9, s[6:7]
	s_add_u32 s39, s39, s9
	s_min_u32 s9, s39, 0xbc0
	s_lshl2_add_u32 s44, s9, s33
	v_ashrrev_i32_e32 v80, 31, v31
	v_or_b32_e32 v80, 0x80000000, v80
	v_xor_b32_e32 v31, v31, v80
	v_lshrrev_b32_e32 v80, 20, v31
	v_cmp_lt_u32_e64 s[10:11], s73, v80
	v_cmp_eq_u32_e64 s[14:15], s73, v80
	v_or_b32_e32 v81, 1, v79
	s_bcnt1_i32_b64 s8, s[10:11]
	v_mbcnt_lo_u32_b32 v82, s10, 0
	v_mbcnt_hi_u32_b32 v82, s11, v82
	v_lshl_add_u32 v82, v82, 2, s42
	s_mov_b64 exec, s[10:11]
	ds_write_b32 v82, v81 offset:16384
	s_mov_b64 exec, s[14:15]
	v_mbcnt_lo_u32_b32 v83, s14, 0
	v_mbcnt_hi_u32_b32 v83, s15, v83
	v_lshl_add_u32 v83, v83, 2, s44
	ds_write2st64_b32 v83, v31, v81 offset1:16
	s_mov_b64 exec, -1
	s_add_u32 s24, s24, s8
	s_lshl2_add_u32 s42, s8, s42
	s_bcnt1_i32_b64 s9, s[14:15]
	s_add_u32 s39, s39, s9
	s_min_u32 s9, s39, 0xbc0
	s_lshl2_add_u32 s44, s9, s33
	v_ashrrev_i32_e32 v75, 31, v32
	v_or_b32_e32 v75, 0x80000000, v75
	v_xor_b32_e32 v32, v32, v75
	v_lshrrev_b32_e32 v75, 20, v32
	v_cmp_lt_u32_e64 s[4:5], s73, v75
	v_cmp_eq_u32_e64 s[6:7], s73, v75
	v_or_b32_e32 v76, 2, v79
	s_bcnt1_i32_b64 s8, s[4:5]
	v_mbcnt_lo_u32_b32 v77, s4, 0
	v_mbcnt_hi_u32_b32 v77, s5, v77
	v_lshl_add_u32 v77, v77, 2, s42
	s_mov_b64 exec, s[4:5]
	ds_write_b32 v77, v76 offset:16384
	s_mov_b64 exec, s[6:7]
	v_mbcnt_lo_u32_b32 v78, s6, 0
	v_mbcnt_hi_u32_b32 v78, s7, v78
	v_lshl_add_u32 v78, v78, 2, s44
	ds_write2st64_b32 v78, v32, v76 offset1:16
	s_mov_b64 exec, -1
	s_add_u32 s24, s24, s8
	s_lshl2_add_u32 s42, s8, s42
	s_bcnt1_i32_b64 s9, s[6:7]
	s_add_u32 s39, s39, s9
	s_min_u32 s9, s39, 0xbc0
	s_lshl2_add_u32 s44, s9, s33
	v_ashrrev_i32_e32 v80, 31, v33
	v_or_b32_e32 v80, 0x80000000, v80
	v_xor_b32_e32 v33, v33, v80
	v_lshrrev_b32_e32 v80, 20, v33
	v_cmp_lt_u32_e64 s[10:11], s73, v80
	v_cmp_eq_u32_e64 s[14:15], s73, v80
	v_or_b32_e32 v81, 3, v79
	s_bcnt1_i32_b64 s8, s[10:11]
	v_mbcnt_lo_u32_b32 v82, s10, 0
	v_mbcnt_hi_u32_b32 v82, s11, v82
	v_lshl_add_u32 v82, v82, 2, s42
	s_mov_b64 exec, s[10:11]
	ds_write_b32 v82, v81 offset:16384
	s_mov_b64 exec, s[14:15]
	v_mbcnt_lo_u32_b32 v83, s14, 0
	v_mbcnt_hi_u32_b32 v83, s15, v83
	v_lshl_add_u32 v83, v83, 2, s44
	ds_write2st64_b32 v83, v33, v81 offset1:16
	s_mov_b64 exec, -1
	s_add_u32 s24, s24, s8
	s_lshl2_add_u32 s42, s8, s42
	s_bcnt1_i32_b64 s9, s[14:15]
	s_add_u32 s39, s39, s9
	s_min_u32 s9, s39, 0xbc0
	s_lshl2_add_u32 s44, s9, s33
	s_cmp_eq_u32 s1, 8
	s_cbranch_scc1 .Lsel2_done
	v_add_u32_e32 v79, 0x900, v73
	v_ashrrev_i32_e32 v75, 31, v26
	v_or_b32_e32 v75, 0x80000000, v75
	v_xor_b32_e32 v26, v26, v75
	v_lshrrev_b32_e32 v75, 20, v26
	v_cmp_lt_u32_e64 s[4:5], s73, v75
	v_cmp_eq_u32_e64 s[6:7], s73, v75
	s_bcnt1_i32_b64 s8, s[4:5]
	v_mbcnt_lo_u32_b32 v77, s4, 0
	v_mbcnt_hi_u32_b32 v77, s5, v77
	v_lshl_add_u32 v77, v77, 2, s42
	s_mov_b64 exec, s[4:5]
	ds_write_b32 v77, v79 offset:16384
	s_mov_b64 exec, s[6:7]
	v_mbcnt_lo_u32_b32 v78, s6, 0
	v_mbcnt_hi_u32_b32 v78, s7, v78
	v_lshl_add_u32 v78, v78, 2, s44
	ds_write2st64_b32 v78, v26, v79 offset1:16
	s_mov_b64 exec, -1
	s_add_u32 s24, s24, s8
	s_lshl2_add_u32 s42, s8, s42
	s_bcnt1_i32_b64 s9, s[6:7]
	s_add_u32 s39, s39, s9
	s_min_u32 s9, s39, 0xbc0
	s_lshl2_add_u32 s44, s9, s33
	v_ashrrev_i32_e32 v80, 31, v27
	v_or_b32_e32 v80, 0x80000000, v80
	v_xor_b32_e32 v27, v27, v80
	v_lshrrev_b32_e32 v80, 20, v27
	v_cmp_lt_u32_e64 s[10:11], s73, v80
	v_cmp_eq_u32_e64 s[14:15], s73, v80
	v_or_b32_e32 v81, 1, v79
	s_bcnt1_i32_b64 s8, s[10:11]
	v_mbcnt_lo_u32_b32 v82, s10, 0
	v_mbcnt_hi_u32_b32 v82, s11, v82
	v_lshl_add_u32 v82, v82, 2, s42
	s_mov_b64 exec, s[10:11]
	ds_write_b32 v82, v81 offset:16384
	s_mov_b64 exec, s[14:15]
	v_mbcnt_lo_u32_b32 v83, s14, 0
	v_mbcnt_hi_u32_b32 v83, s15, v83
	v_lshl_add_u32 v83, v83, 2, s44
	ds_write2st64_b32 v83, v27, v81 offset1:16
	s_mov_b64 exec, -1
	s_add_u32 s24, s24, s8
	s_lshl2_add_u32 s42, s8, s42
	s_bcnt1_i32_b64 s9, s[14:15]
	s_add_u32 s39, s39, s9
	s_min_u32 s9, s39, 0xbc0
	s_lshl2_add_u32 s44, s9, s33
	v_ashrrev_i32_e32 v75, 31, v28
	v_or_b32_e32 v75, 0x80000000, v75
	v_xor_b32_e32 v28, v28, v75
	v_lshrrev_b32_e32 v75, 20, v28
	v_cmp_lt_u32_e64 s[4:5], s73, v75
	v_cmp_eq_u32_e64 s[6:7], s73, v75
	v_or_b32_e32 v76, 2, v79
	s_bcnt1_i32_b64 s8, s[4:5]
	v_mbcnt_lo_u32_b32 v77, s4, 0
	v_mbcnt_hi_u32_b32 v77, s5, v77
	v_lshl_add_u32 v77, v77, 2, s42
	s_mov_b64 exec, s[4:5]
	ds_write_b32 v77, v76 offset:16384
	s_mov_b64 exec, s[6:7]
	v_mbcnt_lo_u32_b32 v78, s6, 0
	v_mbcnt_hi_u32_b32 v78, s7, v78
	v_lshl_add_u32 v78, v78, 2, s44
	ds_write2st64_b32 v78, v28, v76 offset1:16
	s_mov_b64 exec, -1
	s_add_u32 s24, s24, s8
	s_lshl2_add_u32 s42, s8, s42
	s_bcnt1_i32_b64 s9, s[6:7]
	s_add_u32 s39, s39, s9
	s_min_u32 s9, s39, 0xbc0
	s_lshl2_add_u32 s44, s9, s33
	v_ashrrev_i32_e32 v80, 31, v29
	v_or_b32_e32 v80, 0x80000000, v80
	v_xor_b32_e32 v29, v29, v80
	v_lshrrev_b32_e32 v80, 20, v29
	v_cmp_lt_u32_e64 s[10:11], s73, v80
	v_cmp_eq_u32_e64 s[14:15], s73, v80
	v_or_b32_e32 v81, 3, v79
	s_bcnt1_i32_b64 s8, s[10:11]
	v_mbcnt_lo_u32_b32 v82, s10, 0
	v_mbcnt_hi_u32_b32 v82, s11, v82
	v_lshl_add_u32 v82, v82, 2, s42
	s_mov_b64 exec, s[10:11]
	ds_write_b32 v82, v81 offset:16384
	s_mov_b64 exec, s[14:15]
	v_mbcnt_lo_u32_b32 v83, s14, 0
	v_mbcnt_hi_u32_b32 v83, s15, v83
	v_lshl_add_u32 v83, v83, 2, s44
	ds_write2st64_b32 v83, v29, v81 offset1:16
	s_mov_b64 exec, -1
	s_add_u32 s24, s24, s8
	s_lshl2_add_u32 s42, s8, s42
	s_bcnt1_i32_b64 s9, s[14:15]
	s_add_u32 s39, s39, s9
	s_min_u32 s9, s39, 0xbc0
	s_lshl2_add_u32 s44, s9, s33
	s_cmp_eq_u32 s1, 9
	s_cbranch_scc1 .Lsel2_done
; __device__ __forceinline__ unsigned f2key(float f) { const unsigned u = __float_as_uint(f); return (u & 0x80000000u) ? ~u : (u | 0x80000000u); }
; #define SEL_LOAD4(v_, i0_) do { _Pragma("unroll") for (int q = 0; q < 16; ++q) { const int i_ = (i0_) + 256 * q + 4 * lane; v_[q] = (i_ < n) ? srow4[i_ >> 2] : (f32x4){0.f, 0.f, 0.f, 0.f}; } } while (0)
; __device__ __forceinline__ void select256(LAS unsigned char* wl, const float* srow, int n, int lane) {
;     ...
;     for (int i0 = 0; i0 < n; i0 += 4096) {
;         f32x4 v[16]; SEL_LOAD4(v, i0);
; #pragma unroll
;         for (int q = 0; q < 16; ++q)
; #pragma unroll
;             for (int e = 0; e < 4; ++e) {
;                 const int i = i0 + 256 * q + 4 * lane + e; const bool in = i < n; const unsigned key = f2key(v[q][e]); const unsigned bin = key >> 20;
;                 const bool gt = in && bin > b1, eq = in && bin == b1;
;                 const unsigned long long bg = __ballot(gt), be = __ballot(eq);
;                 if (gt) { const unsigned pos = run + (unsigned)__popcll(bg & lt); if (pos < 256u) idx[pos] = i; }
;                 if (eq) { const unsigned pos = cc + (unsigned)__popcll(be & lt); if (pos < (unsigned)CAP) { candk[pos] = key; candi[pos] = i; } }
;                 run += (unsigned)__popcll(bg); cc += (unsigned)__popcll(be);
;             }
;     }
	v_add_u32_e32 v79, 0xa00, v73
	v_ashrrev_i32_e32 v75, 31, v22
	v_or_b32_e32 v75, 0x80000000, v75
	v_xor_b32_e32 v22, v22, v75
	v_lshrrev_b32_e32 v75, 20, v22
	v_cmp_lt_u32_e64 s[4:5], s73, v75
	v_cmp_eq_u32_e64 s[6:7], s73, v75
	s_bcnt1_i32_b64 s8, s[4:5]
	v_mbcnt_lo_u32_b32 v77, s4, 0
	v_mbcnt_hi_u32_b32 v77, s5, v77
	v_lshl_add_u32 v77, v77, 2, s42
	s_mov_b64 exec, s[4:5]
	ds_write_b32 v77, v79 offset:16384
	s_mov_b64 exec, s[6:7]
	v_mbcnt_lo_u32_b32 v78, s6, 0
	v_mbcnt_hi_u32_b32 v78, s7, v78
	v_lshl_add_u32 v78, v78, 2, s44
	ds_write2st64_b32 v78, v22, v79 offset1:16
	s_mov_b64 exec, -1
	s_add_u32 s24, s24, s8
	s_lshl2_add_u32 s42, s8, s42
	s_bcnt1_i32_b64 s9, s[6:7]
	s_add_u32 s39, s39, s9
	s_min_u32 s9, s39, 0xbc0
	s_lshl2_add_u32 s44, s9, s33
	v_ashrrev_i32_e32 v80, 31, v23
	v_or_b32_e32 v80, 0x80000000, v80
	v_xor_b32_e32 v23, v23, v80
	v_lshrrev_b32_e32 v80, 20, v23
	v_cmp_lt_u32_e64 s[10:11], s73, v80
	v_cmp_eq_u32_e64 s[14:15], s73, v80
	v_or_b32_e32 v81, 1, v79
	s_bcnt1_i32_b64 s8, s[10:11]
	v_mbcnt_lo_u32_b32 v82, s10, 0
	v_mbcnt_hi_u32_b32 v82, s11, v82
	v_lshl_add_u32 v82, v82, 2, s42
	s_mov_b64 exec, s[10:11]
	ds_write_b32 v82, v81 offset:16384
	s_mov_b64 exec, s[14:15]
	v_mbcnt_lo_u32_b32 v83, s14, 0
	v_mbcnt_hi_u32_b32 v83, s15, v83
	v_lshl_add_u32 v83, v83, 2, s44
	ds_write2st64_b32 v83, v23, v81 offset1:16
	s_mov_b64 exec, -1
	s_add_u32 s24, s24, s8
	s_lshl2_add_u32 s42, s8, s42
	s_bcnt1_i32_b64 s9, s[14:15]
	s_add_u32 s39, s39, s9
	s_min_u32 s9, s39, 0xbc0
	s_lshl2_add_u32 s44, s9, s33
	v_ashrrev_i32_e32 v75, 31, v24
	v_or_b32_e32 v75, 0x80000000, v75
	v_xor_b32_e32 v24, v24, v75
	v_lshrrev_b32_e32 v75, 20, v24
	v_cmp_lt_u32_e64 s[4:5], s73, v75
	v_cmp_eq_u32_e64 s[6:7], s73, v75
	v_or_b32_e32 v76, 2, v79
	s_bcnt1_i32_b64 s8, s[4:5]
	v_mbcnt_lo_u32_b32 v77, s4, 0
	v_mbcnt_hi_u32_b32 v77, s5, v77
	v_lshl_add_u32 v77, v77, 2, s42
	s_mov_b64 exec, s[4:5]
	ds_write_b32 v77, v76 offset:16384
	s_mov_b64 exec, s[6:7]
	v_mbcnt_lo_u32_b32 v78, s6, 0
	v_mbcnt_hi_u32_b32 v78, s7, v78
	v_lshl_add_u32 v78, v78, 2, s44
	ds_write2st64_b32 v78, v24, v76 offset1:16
	s_mov_b64 exec, -1
	s_add_u32 s24, s24, s8
	s_lshl2_add_u32 s42, s8, s42
	s_bcnt1_i32_b64 s9, s[6:7]
	s_add_u32 s39, s39, s9
	s_min_u32 s9, s39, 0xbc0
	s_lshl2_add_u32 s44, s9, s33
	v_ashrrev_i32_e32 v80, 31, v25
	v_or_b32_e32 v80, 0x80000000, v80
	v_xor_b32_e32 v25, v25, v80
	v_lshrrev_b32_e32 v80, 20, v25
	v_cmp_lt_u32_e64 s[10:11], s73, v80
	v_cmp_eq_u32_e64 s[14:15], s73, v80
	v_or_b32_e32 v81, 3, v79
	s_bcnt1_i32_b64 s8, s[10:11]
	v_mbcnt_lo_u32_b32 v82, s10, 0
	v_mbcnt_hi_u32_b32 v82, s11, v82
	v_lshl_add_u32 v82, v82, 2, s42
	s_mov_b64 exec, s[10:11]
	ds_write_b32 v82, v81 offset:16384
	s_mov_b64 exec, s[14:15]
	v_mbcnt_lo_u32_b32 v83, s14, 0
	v_mbcnt_hi_u32_b32 v83, s15, v83
	v_lshl_add_u32 v83, v83, 2, s44
	ds_write2st64_b32 v83, v25, v81 offset1:16
	s_mov_b64 exec, -1
	s_add_u32 s24, s24, s8
	s_lshl2_add_u32 s42, s8, s42
	s_bcnt1_i32_b64 s9, s[14:15]
	s_add_u32 s39, s39, s9
	s_min_u32 s9, s39, 0xbc0
	s_lshl2_add_u32 s44, s9, s33
	s_cmp_eq_u32 s1, 10
	s_cbranch_scc1 .Lsel2_done
	v_add_u32_e32 v79, 0xb00, v73
	v_ashrrev_i32_e32 v75, 31, v18
	v_or_b32_e32 v75, 0x80000000, v75
	v_xor_b32_e32 v18, v18, v75
	v_lshrrev_b32_e32 v75, 20, v18
	v_cmp_lt_u32_e64 s[4:5], s73, v75
	v_cmp_eq_u32_e64 s[6:7], s73, v75
	s_bcnt1_i32_b64 s8, s[4:5]
	v_mbcnt_lo_u32_b32 v77, s4, 0
	v_mbcnt_hi_u32_b32 v77, s5, v77
	v_lshl_add_u32 v77, v77, 2, s42
	s_mov_b64 exec, s[4:5]
	ds_write_b32 v77, v79 offset:16384
	s_mov_b64 exec, s[6:7]
	v_mbcnt_lo_u32_b32 v78, s6, 0
	v_mbcnt_hi_u32_b32 v78, s7, v78
	v_lshl_add_u32 v78, v78, 2, s44
	ds_write2st64_b32 v78, v18, v79 offset1:16
	s_mov_b64 exec, -1
	s_add_u32 s24, s24, s8
	s_lshl2_add_u32 s42, s8, s42
	s_bcnt1_i32_b64 s9, s[6:7]
	s_add_u32 s39, s39, s9
	s_min_u32 s9, s39, 0xbc0
	s_lshl2_add_u32 s44, s9, s33
	v_ashrrev_i32_e32 v80, 31, v19
	v_or_b32_e32 v80, 0x80000000, v80
	v_xor_b32_e32 v19, v19, v80
	v_lshrrev_b32_e32 v80, 20, v19
	v_cmp_lt_u32_e64 s[10:11], s73, v80
	v_cmp_eq_u32_e64 s[14:15], s73, v80
	v_or_b32_e32 v81, 1, v79
	s_bcnt1_i32_b64 s8, s[10:11]
	v_mbcnt_lo_u32_b32 v82, s10, 0
	v_mbcnt_hi_u32_b32 v82, s11, v82
	v_lshl_add_u32 v82, v82, 2, s42
	s_mov_b64 exec, s[10:11]
	ds_write_b32 v82, v81 offset:16384
	s_mov_b64 exec, s[14:15]
	v_mbcnt_lo_u32_b32 v83, s14, 0
	v_mbcnt_hi_u32_b32 v83, s15, v83
	v_lshl_add_u32 v83, v83, 2, s44
	ds_write2st64_b32 v83, v19, v81 offset1:16
	s_mov_b64 exec, -1
	s_add_u32 s24, s24, s8
	s_lshl2_add_u32 s42, s8, s42
	s_bcnt1_i32_b64 s9, s[14:15]
	s_add_u32 s39, s39, s9
	s_min_u32 s9, s39, 0xbc0
	s_lshl2_add_u32 s44, s9, s33
	v_ashrrev_i32_e32 v75, 31, v20
	v_or_b32_e32 v75, 0x80000000, v75
	v_xor_b32_e32 v20, v20, v75
	v_lshrrev_b32_e32 v75, 20, v20
	v_cmp_lt_u32_e64 s[4:5], s73, v75
	v_cmp_eq_u32_e64 s[6:7], s73, v75
	v_or_b32_e32 v76, 2, v79
	s_bcnt1_i32_b64 s8, s[4:5]
	v_mbcnt_lo_u32_b32 v77, s4, 0
	v_mbcnt_hi_u32_b32 v77, s5, v77
	v_lshl_add_u32 v77, v77, 2, s42
	s_mov_b64 exec, s[4:5]
	ds_write_b32 v77, v76 offset:16384
	s_mov_b64 exec, s[6:7]
	v_mbcnt_lo_u32_b32 v78, s6, 0
	v_mbcnt_hi_u32_b32 v78, s7, v78
	v_lshl_add_u32 v78, v78, 2, s44
	ds_write2st64_b32 v78, v20, v76 offset1:16
	s_mov_b64 exec, -1
	s_add_u32 s24, s24, s8
	s_lshl2_add_u32 s42, s8, s42
	s_bcnt1_i32_b64 s9, s[6:7]
	s_add_u32 s39, s39, s9
	s_min_u32 s9, s39, 0xbc0
	s_lshl2_add_u32 s44, s9, s33
	v_ashrrev_i32_e32 v80, 31, v21
	v_or_b32_e32 v80, 0x80000000, v80
	v_xor_b32_e32 v21, v21, v80
	v_lshrrev_b32_e32 v80, 20, v21
	v_cmp_lt_u32_e64 s[10:11], s73, v80
	v_cmp_eq_u32_e64 s[14:15], s73, v80
	v_or_b32_e32 v81, 3, v79
	s_bcnt1_i32_b64 s8, s[10:11]
	v_mbcnt_lo_u32_b32 v82, s10, 0
	v_mbcnt_hi_u32_b32 v82, s11, v82
	v_lshl_add_u32 v82, v82, 2, s42
	s_mov_b64 exec, s[10:11]
	ds_write_b32 v82, v81 offset:16384
	s_mov_b64 exec, s[14:15]
	v_mbcnt_lo_u32_b32 v83, s14, 0
	v_mbcnt_hi_u32_b32 v83, s15, v83
	v_lshl_add_u32 v83, v83, 2, s44
	ds_write2st64_b32 v83, v21, v81 offset1:16
	s_mov_b64 exec, -1
	s_add_u32 s24, s24, s8
	s_lshl2_add_u32 s42, s8, s42
	s_bcnt1_i32_b64 s9, s[14:15]
	s_add_u32 s39, s39, s9
	s_min_u32 s9, s39, 0xbc0
	s_lshl2_add_u32 s44, s9, s33
	s_cmp_eq_u32 s1, 11
	s_cbranch_scc1 .Lsel2_done
; __device__ __forceinline__ unsigned f2key(float f) { const unsigned u = __float_as_uint(f); return (u & 0x80000000u) ? ~u : (u | 0x80000000u); }
; #define SEL_LOAD4(v_, i0_) do { _Pragma("unroll") for (int q = 0; q < 16; ++q) { const int i_ = (i0_) + 256 * q + 4 * lane; v_[q] = (i_ < n) ? srow4[i_ >> 2] : (f32x4){0.f, 0.f, 0.f, 0.f}; } } while (0)
; __device__ __forceinline__ void select256(LAS unsigned char* wl, const float* srow, int n, int lane) {
;     ...
;     for (int i0 = 0; i0 < n; i0 += 4096) {
;         f32x4 v[16]; SEL_LOAD4(v, i0);
; #pragma unroll
;         for (int q = 0; q < 16; ++q)
; #pragma unroll
;             for (int e = 0; e < 4; ++e) {
;                 const int i = i0 + 256 * q + 4 * lane + e; const bool in = i < n; const unsigned key = f2key(v[q][e]); const unsigned bin = key >> 20;
;                 const bool gt = in && bin > b1, eq = in && bin == b1;
;                 const unsigned long long bg = __ballot(gt), be = __ballot(eq);
;                 if (gt) { const unsigned pos = run + (unsigned)__popcll(bg & lt); if (pos < 256u) idx[pos] = i; }
;                 if (eq) { const unsigned pos = cc + (unsigned)__popcll(be & lt); if (pos < (unsigned)CAP) { candk[pos] = key; candi[pos] = i; } }
;                 run += (unsigned)__popcll(bg); cc += (unsigned)__popcll(be);
;             }
;     }
	v_add_u32_e32 v79, 0xc00, v73
	v_ashrrev_i32_e32 v75, 31, v14
	v_or_b32_e32 v75, 0x80000000, v75
	v_xor_b32_e32 v14, v14, v75
	v_lshrrev_b32_e32 v75, 20, v14
	v_cmp_lt_u32_e64 s[4:5], s73, v75
	v_cmp_eq_u32_e64 s[6:7], s73, v75
	s_bcnt1_i32_b64 s8, s[4:5]
	v_mbcnt_lo_u32_b32 v77, s4, 0
	v_mbcnt_hi_u32_b32 v77, s5, v77
	v_lshl_add_u32 v77, v77, 2, s42
	s_mov_b64 exec, s[4:5]
	ds_write_b32 v77, v79 offset:16384
	s_mov_b64 exec, s[6:7]
	v_mbcnt_lo_u32_b32 v78, s6, 0
	v_mbcnt_hi_u32_b32 v78, s7, v78
	v_lshl_add_u32 v78, v78, 2, s44
	ds_write2st64_b32 v78, v14, v79 offset1:16
	s_mov_b64 exec, -1
	s_add_u32 s24, s24, s8
	s_lshl2_add_u32 s42, s8, s42
	s_bcnt1_i32_b64 s9, s[6:7]
	s_add_u32 s39, s39, s9
	s_min_u32 s9, s39, 0xbc0
	s_lshl2_add_u32 s44, s9, s33
	v_ashrrev_i32_e32 v80, 31, v15
	v_or_b32_e32 v80, 0x80000000, v80
	v_xor_b32_e32 v15, v15, v80
	v_lshrrev_b32_e32 v80, 20, v15
	v_cmp_lt_u32_e64 s[10:11], s73, v80
	v_cmp_eq_u32_e64 s[14:15], s73, v80
	v_or_b32_e32 v81, 1, v79
	s_bcnt1_i32_b64 s8, s[10:11]
	v_mbcnt_lo_u32_b32 v82, s10, 0
	v_mbcnt_hi_u32_b32 v82, s11, v82
	v_lshl_add_u32 v82, v82, 2, s42
	s_mov_b64 exec, s[10:11]
	ds_write_b32 v82, v81 offset:16384
	s_mov_b64 exec, s[14:15]
	v_mbcnt_lo_u32_b32 v83, s14, 0
	v_mbcnt_hi_u32_b32 v83, s15, v83
	v_lshl_add_u32 v83, v83, 2, s44
	ds_write2st64_b32 v83, v15, v81 offset1:16
	s_mov_b64 exec, -1
	s_add_u32 s24, s24, s8
	s_lshl2_add_u32 s42, s8, s42
	s_bcnt1_i32_b64 s9, s[14:15]
	s_add_u32 s39, s39, s9
	s_min_u32 s9, s39, 0xbc0
	s_lshl2_add_u32 s44, s9, s33
	v_ashrrev_i32_e32 v75, 31, v16
	v_or_b32_e32 v75, 0x80000000, v75
	v_xor_b32_e32 v16, v16, v75
	v_lshrrev_b32_e32 v75, 20, v16
	v_cmp_lt_u32_e64 s[4:5], s73, v75
	v_cmp_eq_u32_e64 s[6:7], s73, v75
	v_or_b32_e32 v76, 2, v79
	s_bcnt1_i32_b64 s8, s[4:5]
	v_mbcnt_lo_u32_b32 v77, s4, 0
	v_mbcnt_hi_u32_b32 v77, s5, v77
	v_lshl_add_u32 v77, v77, 2, s42
	s_mov_b64 exec, s[4:5]
	ds_write_b32 v77, v76 offset:16384
	s_mov_b64 exec, s[6:7]
	v_mbcnt_lo_u32_b32 v78, s6, 0
	v_mbcnt_hi_u32_b32 v78, s7, v78
	v_lshl_add_u32 v78, v78, 2, s44
	ds_write2st64_b32 v78, v16, v76 offset1:16
	s_mov_b64 exec, -1
	s_add_u32 s24, s24, s8
	s_lshl2_add_u32 s42, s8, s42
	s_bcnt1_i32_b64 s9, s[6:7]
	s_add_u32 s39, s39, s9
	s_min_u32 s9, s39, 0xbc0
	s_lshl2_add_u32 s44, s9, s33
	v_ashrrev_i32_e32 v80, 31, v17
	v_or_b32_e32 v80, 0x80000000, v80
	v_xor_b32_e32 v17, v17, v80
	v_lshrrev_b32_e32 v80, 20, v17
	v_cmp_lt_u32_e64 s[10:11], s73, v80
	v_cmp_eq_u32_e64 s[14:15], s73, v80
	v_or_b32_e32 v81, 3, v79
	s_bcnt1_i32_b64 s8, s[10:11]
	v_mbcnt_lo_u32_b32 v82, s10, 0
	v_mbcnt_hi_u32_b32 v82, s11, v82
	v_lshl_add_u32 v82, v82, 2, s42
	s_mov_b64 exec, s[10:11]
	ds_write_b32 v82, v81 offset:16384
	s_mov_b64 exec, s[14:15]
	v_mbcnt_lo_u32_b32 v83, s14, 0
	v_mbcnt_hi_u32_b32 v83, s15, v83
	v_lshl_add_u32 v83, v83, 2, s44
	ds_write2st64_b32 v83, v17, v81 offset1:16
	s_mov_b64 exec, -1
	s_add_u32 s24, s24, s8
	s_lshl2_add_u32 s42, s8, s42
	s_bcnt1_i32_b64 s9, s[14:15]
	s_add_u32 s39, s39, s9
	s_min_u32 s9, s39, 0xbc0
	s_lshl2_add_u32 s44, s9, s33
	s_cmp_eq_u32 s1, 12
	s_cbranch_scc1 .Lsel2_done
	v_add_u32_e32 v79, 0xd00, v73
	v_ashrrev_i32_e32 v75, 31, v10
	v_or_b32_e32 v75, 0x80000000, v75
	v_xor_b32_e32 v10, v10, v75
	v_lshrrev_b32_e32 v75, 20, v10
	v_cmp_lt_u32_e64 s[4:5], s73, v75
	v_cmp_eq_u32_e64 s[6:7], s73, v75
	s_bcnt1_i32_b64 s8, s[4:5]
	v_mbcnt_lo_u32_b32 v77, s4, 0
	v_mbcnt_hi_u32_b32 v77, s5, v77
	v_lshl_add_u32 v77, v77, 2, s42
	s_mov_b64 exec, s[4:5]
	ds_write_b32 v77, v79 offset:16384
	s_mov_b64 exec, s[6:7]
	v_mbcnt_lo_u32_b32 v78, s6, 0
	v_mbcnt_hi_u32_b32 v78, s7, v78
	v_lshl_add_u32 v78, v78, 2, s44
	ds_write2st64_b32 v78, v10, v79 offset1:16
	s_mov_b64 exec, -1
	s_add_u32 s24, s24, s8
	s_lshl2_add_u32 s42, s8, s42
	s_bcnt1_i32_b64 s9, s[6:7]
	s_add_u32 s39, s39, s9
	s_min_u32 s9, s39, 0xbc0
	s_lshl2_add_u32 s44, s9, s33
	v_ashrrev_i32_e32 v80, 31, v11
	v_or_b32_e32 v80, 0x80000000, v80
	v_xor_b32_e32 v11, v11, v80
	v_lshrrev_b32_e32 v80, 20, v11
	v_cmp_lt_u32_e64 s[10:11], s73, v80
	v_cmp_eq_u32_e64 s[14:15], s73, v80
	v_or_b32_e32 v81, 1, v79
	s_bcnt1_i32_b64 s8, s[10:11]
	v_mbcnt_lo_u32_b32 v82, s10, 0
	v_mbcnt_hi_u32_b32 v82, s11, v82
	v_lshl_add_u32 v82, v82, 2, s42
	s_mov_b64 exec, s[10:11]
	ds_write_b32 v82, v81 offset:16384
	s_mov_b64 exec, s[14:15]
	v_mbcnt_lo_u32_b32 v83, s14, 0
	v_mbcnt_hi_u32_b32 v83, s15, v83
	v_lshl_add_u32 v83, v83, 2, s44
	ds_write2st64_b32 v83, v11, v81 offset1:16
	s_mov_b64 exec, -1
	s_add_u32 s24, s24, s8
	s_lshl2_add_u32 s42, s8, s42
	s_bcnt1_i32_b64 s9, s[14:15]
	s_add_u32 s39, s39, s9
	s_min_u32 s9, s39, 0xbc0
	s_lshl2_add_u32 s44, s9, s33
	v_ashrrev_i32_e32 v75, 31, v12
	v_or_b32_e32 v75, 0x80000000, v75
	v_xor_b32_e32 v12, v12, v75
	v_lshrrev_b32_e32 v75, 20, v12
	v_cmp_lt_u32_e64 s[4:5], s73, v75
	v_cmp_eq_u32_e64 s[6:7], s73, v75
	v_or_b32_e32 v76, 2, v79
	s_bcnt1_i32_b64 s8, s[4:5]
	v_mbcnt_lo_u32_b32 v77, s4, 0
	v_mbcnt_hi_u32_b32 v77, s5, v77
	v_lshl_add_u32 v77, v77, 2, s42
	s_mov_b64 exec, s[4:5]
	ds_write_b32 v77, v76 offset:16384
	s_mov_b64 exec, s[6:7]
	v_mbcnt_lo_u32_b32 v78, s6, 0
	v_mbcnt_hi_u32_b32 v78, s7, v78
	v_lshl_add_u32 v78, v78, 2, s44
	ds_write2st64_b32 v78, v12, v76 offset1:16
	s_mov_b64 exec, -1
	s_add_u32 s24, s24, s8
	s_lshl2_add_u32 s42, s8, s42
	s_bcnt1_i32_b64 s9, s[6:7]
	s_add_u32 s39, s39, s9
	s_min_u32 s9, s39, 0xbc0
	s_lshl2_add_u32 s44, s9, s33
	v_ashrrev_i32_e32 v80, 31, v13
	v_or_b32_e32 v80, 0x80000000, v80
	v_xor_b32_e32 v13, v13, v80
	v_lshrrev_b32_e32 v80, 20, v13
	v_cmp_lt_u32_e64 s[10:11], s73, v80
	v_cmp_eq_u32_e64 s[14:15], s73, v80
	v_or_b32_e32 v81, 3, v79
	s_bcnt1_i32_b64 s8, s[10:11]
	v_mbcnt_lo_u32_b32 v82, s10, 0
	v_mbcnt_hi_u32_b32 v82, s11, v82
	v_lshl_add_u32 v82, v82, 2, s42
	s_mov_b64 exec, s[10:11]
	ds_write_b32 v82, v81 offset:16384
	s_mov_b64 exec, s[14:15]
	v_mbcnt_lo_u32_b32 v83, s14, 0
	v_mbcnt_hi_u32_b32 v83, s15, v83
	v_lshl_add_u32 v83, v83, 2, s44
	ds_write2st64_b32 v83, v13, v81 offset1:16
	s_mov_b64 exec, -1
	s_add_u32 s24, s24, s8
	s_lshl2_add_u32 s42, s8, s42
	s_bcnt1_i32_b64 s9, s[14:15]
	s_add_u32 s39, s39, s9
	s_min_u32 s9, s39, 0xbc0
	s_lshl2_add_u32 s44, s9, s33
	s_cmp_eq_u32 s1, 13
	s_cbranch_scc1 .Lsel2_done
; __device__ __forceinline__ unsigned f2key(float f) { const unsigned u = __float_as_uint(f); return (u & 0x80000000u) ? ~u : (u | 0x80000000u); }
; #define SEL_LOAD4(v_, i0_) do { _Pragma("unroll") for (int q = 0; q < 16; ++q) { const int i_ = (i0_) + 256 * q + 4 * lane; v_[q] = (i_ < n) ? srow4[i_ >> 2] : (f32x4){0.f, 0.f, 0.f, 0.f}; } } while (0)
; __device__ __forceinline__ void select256(LAS unsigned char* wl, const float* srow, int n, int lane) {
;     ...
;     for (int i0 = 0; i0 < n; i0 += 4096) {
;         f32x4 v[16]; SEL_LOAD4(v, i0);
; #pragma unroll
;         for (int q = 0; q < 16; ++q)
; #pragma unroll
;             for (int e = 0; e < 4; ++e) {
;                 const int i = i0 + 256 * q + 4 * lane + e; const bool in = i < n; const unsigned key = f2key(v[q][e]); const unsigned bin = key >> 20;
;                 const bool gt = in && bin > b1, eq = in && bin == b1;
;                 const unsigned long long bg = __ballot(gt), be = __ballot(eq);
;                 if (gt) { const unsigned pos = run + (unsigned)__popcll(bg & lt); if (pos < 256u) idx[pos] = i; }
;                 if (eq) { const unsigned pos = cc + (unsigned)__popcll(be & lt); if (pos < (unsigned)CAP) { candk[pos] = key; candi[pos] = i; } }
;                 run += (unsigned)__popcll(bg); cc += (unsigned)__popcll(be);
;             }
;     }
	v_add_u32_e32 v79, 0xe00, v73
	v_ashrrev_i32_e32 v75, 31, v6
	v_or_b32_e32 v75, 0x80000000, v75
	v_xor_b32_e32 v6, v6, v75
	v_lshrrev_b32_e32 v75, 20, v6
	v_cmp_lt_u32_e64 s[4:5], s73, v75
	v_cmp_eq_u32_e64 s[6:7], s73, v75
	s_bcnt1_i32_b64 s8, s[4:5]
	v_mbcnt_lo_u32_b32 v77, s4, 0
	v_mbcnt_hi_u32_b32 v77, s5, v77
	v_lshl_add_u32 v77, v77, 2, s42
	s_mov_b64 exec, s[4:5]
	ds_write_b32 v77, v79 offset:16384
	s_mov_b64 exec, s[6:7]
	v_mbcnt_lo_u32_b32 v78, s6, 0
	v_mbcnt_hi_u32_b32 v78, s7, v78
	v_lshl_add_u32 v78, v78, 2, s44
	ds_write2st64_b32 v78, v6, v79 offset1:16
	s_mov_b64 exec, -1
	s_add_u32 s24, s24, s8
	s_lshl2_add_u32 s42, s8, s42
	s_bcnt1_i32_b64 s9, s[6:7]
	s_add_u32 s39, s39, s9
	s_min_u32 s9, s39, 0xbc0
	s_lshl2_add_u32 s44, s9, s33
	v_ashrrev_i32_e32 v80, 31, v7
	v_or_b32_e32 v80, 0x80000000, v80
	v_xor_b32_e32 v7, v7, v80
	v_lshrrev_b32_e32 v80, 20, v7
	v_cmp_lt_u32_e64 s[10:11], s73, v80
	v_cmp_eq_u32_e64 s[14:15], s73, v80
	v_or_b32_e32 v81, 1, v79
	s_bcnt1_i32_b64 s8, s[10:11]
	v_mbcnt_lo_u32_b32 v82, s10, 0
	v_mbcnt_hi_u32_b32 v82, s11, v82
	v_lshl_add_u32 v82, v82, 2, s42
	s_mov_b64 exec, s[10:11]
	ds_write_b32 v82, v81 offset:16384
	s_mov_b64 exec, s[14:15]
	v_mbcnt_lo_u32_b32 v83, s14, 0
	v_mbcnt_hi_u32_b32 v83, s15, v83
	v_lshl_add_u32 v83, v83, 2, s44
	ds_write2st64_b32 v83, v7, v81 offset1:16
	s_mov_b64 exec, -1
	s_add_u32 s24, s24, s8
	s_lshl2_add_u32 s42, s8, s42
	s_bcnt1_i32_b64 s9, s[14:15]
	s_add_u32 s39, s39, s9
	s_min_u32 s9, s39, 0xbc0
	s_lshl2_add_u32 s44, s9, s33
	v_ashrrev_i32_e32 v75, 31, v8
	v_or_b32_e32 v75, 0x80000000, v75
	v_xor_b32_e32 v8, v8, v75
	v_lshrrev_b32_e32 v75, 20, v8
	v_cmp_lt_u32_e64 s[4:5], s73, v75
	v_cmp_eq_u32_e64 s[6:7], s73, v75
	v_or_b32_e32 v76, 2, v79
	s_bcnt1_i32_b64 s8, s[4:5]
	v_mbcnt_lo_u32_b32 v77, s4, 0
	v_mbcnt_hi_u32_b32 v77, s5, v77
	v_lshl_add_u32 v77, v77, 2, s42
	s_mov_b64 exec, s[4:5]
	ds_write_b32 v77, v76 offset:16384
	s_mov_b64 exec, s[6:7]
	v_mbcnt_lo_u32_b32 v78, s6, 0
	v_mbcnt_hi_u32_b32 v78, s7, v78
	v_lshl_add_u32 v78, v78, 2, s44
	ds_write2st64_b32 v78, v8, v76 offset1:16
	s_mov_b64 exec, -1
	s_add_u32 s24, s24, s8
	s_lshl2_add_u32 s42, s8, s42
	s_bcnt1_i32_b64 s9, s[6:7]
	s_add_u32 s39, s39, s9
	s_min_u32 s9, s39, 0xbc0
	s_lshl2_add_u32 s44, s9, s33
	v_ashrrev_i32_e32 v80, 31, v9
	v_or_b32_e32 v80, 0x80000000, v80
	v_xor_b32_e32 v9, v9, v80
	v_lshrrev_b32_e32 v80, 20, v9
	v_cmp_lt_u32_e64 s[10:11], s73, v80
	v_cmp_eq_u32_e64 s[14:15], s73, v80
	v_or_b32_e32 v81, 3, v79
	s_bcnt1_i32_b64 s8, s[10:11]
	v_mbcnt_lo_u32_b32 v82, s10, 0
	v_mbcnt_hi_u32_b32 v82, s11, v82
	v_lshl_add_u32 v82, v82, 2, s42
	s_mov_b64 exec, s[10:11]
	ds_write_b32 v82, v81 offset:16384
	s_mov_b64 exec, s[14:15]
	v_mbcnt_lo_u32_b32 v83, s14, 0
	v_mbcnt_hi_u32_b32 v83, s15, v83
	v_lshl_add_u32 v83, v83, 2, s44
	ds_write2st64_b32 v83, v9, v81 offset1:16
	s_mov_b64 exec, -1
	s_add_u32 s24, s24, s8
	s_lshl2_add_u32 s42, s8, s42
	s_bcnt1_i32_b64 s9, s[14:15]
	s_add_u32 s39, s39, s9
	s_min_u32 s9, s39, 0xbc0
	s_lshl2_add_u32 s44, s9, s33
	s_cmp_eq_u32 s1, 14
	s_cbranch_scc1 .Lsel2_done
	v_add_u32_e32 v79, 0xf00, v73
	v_ashrrev_i32_e32 v75, 31, v2
	v_or_b32_e32 v75, 0x80000000, v75
	v_xor_b32_e32 v2, v2, v75
	v_lshrrev_b32_e32 v75, 20, v2
	v_cmp_lt_u32_e64 s[4:5], s73, v75
	v_cmp_eq_u32_e64 s[6:7], s73, v75
	s_bcnt1_i32_b64 s8, s[4:5]
	v_mbcnt_lo_u32_b32 v77, s4, 0
	v_mbcnt_hi_u32_b32 v77, s5, v77
	v_lshl_add_u32 v77, v77, 2, s42
	s_mov_b64 exec, s[4:5]
	ds_write_b32 v77, v79 offset:16384
	s_mov_b64 exec, s[6:7]
	v_mbcnt_lo_u32_b32 v78, s6, 0
	v_mbcnt_hi_u32_b32 v78, s7, v78
	v_lshl_add_u32 v78, v78, 2, s44
	ds_write2st64_b32 v78, v2, v79 offset1:16
	s_mov_b64 exec, -1
	s_add_u32 s24, s24, s8
	s_lshl2_add_u32 s42, s8, s42
	s_bcnt1_i32_b64 s9, s[6:7]
	s_add_u32 s39, s39, s9
	s_min_u32 s9, s39, 0xbc0
	s_lshl2_add_u32 s44, s9, s33
	v_ashrrev_i32_e32 v80, 31, v3
	v_or_b32_e32 v80, 0x80000000, v80
	v_xor_b32_e32 v3, v3, v80
	v_lshrrev_b32_e32 v80, 20, v3
	v_cmp_lt_u32_e64 s[10:11], s73, v80
	v_cmp_eq_u32_e64 s[14:15], s73, v80
	v_or_b32_e32 v81, 1, v79
	s_bcnt1_i32_b64 s8, s[10:11]
	v_mbcnt_lo_u32_b32 v82, s10, 0
	v_mbcnt_hi_u32_b32 v82, s11, v82
	v_lshl_add_u32 v82, v82, 2, s42
	s_mov_b64 exec, s[10:11]
	ds_write_b32 v82, v81 offset:16384
	s_mov_b64 exec, s[14:15]
	v_mbcnt_lo_u32_b32 v83, s14, 0
	v_mbcnt_hi_u32_b32 v83, s15, v83
	v_lshl_add_u32 v83, v83, 2, s44
	ds_write2st64_b32 v83, v3, v81 offset1:16
	s_mov_b64 exec, -1
	s_add_u32 s24, s24, s8
	s_lshl2_add_u32 s42, s8, s42
	s_bcnt1_i32_b64 s9, s[14:15]
	s_add_u32 s39, s39, s9
	s_min_u32 s9, s39, 0xbc0
	s_lshl2_add_u32 s44, s9, s33
	v_ashrrev_i32_e32 v75, 31, v4
	v_or_b32_e32 v75, 0x80000000, v75
	v_xor_b32_e32 v4, v4, v75
	v_lshrrev_b32_e32 v75, 20, v4
	v_cmp_lt_u32_e64 s[4:5], s73, v75
	v_cmp_eq_u32_e64 s[6:7], s73, v75
	v_or_b32_e32 v76, 2, v79
	s_bcnt1_i32_b64 s8, s[4:5]
	v_mbcnt_lo_u32_b32 v77, s4, 0
	v_mbcnt_hi_u32_b32 v77, s5, v77
	v_lshl_add_u32 v77, v77, 2, s42
	s_mov_b64 exec, s[4:5]
	ds_write_b32 v77, v76 offset:16384
	s_mov_b64 exec, s[6:7]
	v_mbcnt_lo_u32_b32 v78, s6, 0
	v_mbcnt_hi_u32_b32 v78, s7, v78
	v_lshl_add_u32 v78, v78, 2, s44
	ds_write2st64_b32 v78, v4, v76 offset1:16
	s_mov_b64 exec, -1
	s_add_u32 s24, s24, s8
	s_lshl2_add_u32 s42, s8, s42
	s_bcnt1_i32_b64 s9, s[6:7]
	s_add_u32 s39, s39, s9
	s_min_u32 s9, s39, 0xbc0
	s_lshl2_add_u32 s44, s9, s33
	v_ashrrev_i32_e32 v80, 31, v5
	v_or_b32_e32 v80, 0x80000000, v80
	v_xor_b32_e32 v5, v5, v80
	v_lshrrev_b32_e32 v80, 20, v5
	v_cmp_lt_u32_e64 s[10:11], s73, v80
	v_cmp_eq_u32_e64 s[14:15], s73, v80
	v_or_b32_e32 v81, 3, v79
	s_bcnt1_i32_b64 s8, s[10:11]
	v_mbcnt_lo_u32_b32 v82, s10, 0
	v_mbcnt_hi_u32_b32 v82, s11, v82
	v_lshl_add_u32 v82, v82, 2, s42
	s_mov_b64 exec, s[10:11]
	ds_write_b32 v82, v81 offset:16384
	s_mov_b64 exec, s[14:15]
	v_mbcnt_lo_u32_b32 v83, s14, 0
	v_mbcnt_hi_u32_b32 v83, s15, v83
	v_lshl_add_u32 v83, v83, 2, s44
	ds_write2st64_b32 v83, v5, v81 offset1:16
	s_mov_b64 exec, -1
	s_add_u32 s24, s24, s8
	s_lshl2_add_u32 s42, s8, s42
	s_bcnt1_i32_b64 s9, s[14:15]
	s_add_u32 s39, s39, s9
	s_min_u32 s9, s39, 0xbc0
	s_lshl2_add_u32 s44, s9, s33
.Lsel2_done:
	s_addk_i32 s38, 0x1000
	s_cmp_ge_u32 s38, s27
	s_cbranch_scc0 .LBB0_753

; #define PG8_WAIT_V(n) asm volatile("s_waitcnt vmcnt(" #n ")" ::: "memory")
; #define PG8_BAR __builtin_amdgcn_s_barrier()
; template <class Epi, class Sched, bool ALIGN_EPI = false, bool SP2 = false>
; __device__ __forceinline__ void gemm_phase(PG8_LAS unsigned char* lds, const Gemm g, const Sched& S, const Epi& E) {
;     ...
;     for (int i = 0; i < 2; ++i) { int R, C; stage_rc(tid * 16 + i * 8192, R, C); const int Rb = Epi::PERM ? ((R & ~31) + perm32(R & 31)) : R;
;         voffA[i] = (unsigned)(R * K + C) * 2u; voffB[i] = (unsigned)(Rb * K + C) * 2u; }
;     const size_t kstep = (size_t)(BK * 2);
;     const size_t hstep = (size_t)HALF * K * 2;
;     const size_t tstep = 2 * hstep;
;     const unsigned ldsw = (unsigned)wid * 1024u;
;     const int aoff = lds_byte(wr * 64 + fr, fq * 8), boff = lds_byte(wc * 32 + fr, fq * 8);
;     ...
;     Unit cur, nxt; int ui = 0;
;     if (!S.next(0, cur)) return;
;     f32x4 acc[2][2][4][2];
; #pragma unroll
;     for (int a = 0; a < 2; ++a)
; #pragma unroll
;         for (int b = 0; b < 2; ++b)
; #pragma unroll
;             for (int m = 0; m < 4; ++m)
; #pragma unroll
;                 for (int n = 0; n < 2; ++n) acc[a][b][m][n] = (f32x4){0.f, 0.f, 0.f, 0.f};
;     bf16x8 At[4][2], B0[2][2], B1[2][2];
;     const char* cA = (const char*)g.A + (size_t)cur.pm * tstep; const char* cB = (const char*)g.Bt + (size_t)cur.pn * tstep;
;     S.a_ready(cur);
;     if constexpr (SP2) {
;         PG8_STAGE(PG8_SB(0, 0), cB, voffB); PG8_STAGE(PG8_SB(0, 1), cB + hstep, voffB); PG8_STAGE(PG8_SA(0, 0), cA, voffA); PG8_STAGE(PG8_SA(0, 1), cA + hstep, voffA);
;         if (wr == 1) PG8_BAR;
;         PG8_WAIT_V(2); PG8_BAR;
;         PG8_STAGE(PG8_SB(1, 0), cB + kstep, voffB); PG8_STAGE(PG8_SA(1, 0), cA + kstep, voffA); PG8_STAGE(PG8_SB(1, 1), cB + hstep + kstep, voffB);
; __global__ void __launch_bounds__(512, 2) mega(Args a) {
;     ...
;                 if (st == 1) {
;                     pg8::Gemm g{xb, (const bf16_t*)(ws + WS_WUP + (size_t)L * 32 * MiB), M, FF, D}; pg8::StaticOrder S; S.init(M, FF, G, (int)blockIdx.x);
;                     pg8::EpiUp E{hid, ss + (size_t)(2 * L + 1) * M, FF};
;     ...
;                     for (int rep_ = 0; rep_ < REP_GUP; ++rep_) pg8::gemm_phase<pg8::EpiUp, pg8::StaticOrder, PG8_ALIGN, PG8_SP2>(lds, g, S, E);
.LBB0_1483:
	s_andn2_b64 vcc, exec, s[0:1]
	s_cbranch_vccnz .LBB0_1504
	v_readlane_b32 s0, v249, 33
	s_waitcnt vmcnt(0)
	v_mov_b32_e32 v8, v171
	v_readlane_b32 s1, v249, 34
	s_andn2_b64 vcc, exec, s[0:1]
	v_readfirstlane_b32 s0, v8
	s_cbranch_vccnz .LBB0_1504
	s_and_b32 s98, s2, 7
	s_cmp_eq_u32 s98, 0
	s_cbranch_scc1 .Lstag_up_done
.Lstag_up_loop:
	s_sleep 32
	s_sub_u32 s98, s98, 1
	s_cmp_lg_u32 s98, 0
	s_cbranch_scc1 .Lstag_up_loop
.Lstag_up_done:
	v_lshlrev_b32_e32 v0, 4, v8
	v_add_u32_e32 v3, 0x2000, v0
	v_ashrrev_i32_e32 v2, 31, v3
	v_lshrrev_b32_e32 v2, 22, v2
	v_add_u32_e32 v2, v3, v2
	v_ashrrev_i32_e32 v2, 10, v2
	v_mul_i32_i24_e32 v4, 0x400, v2
	v_sub_u32_e32 v3, v3, v4
	v_lshrrev_b32_e32 v4, 4, v3
	v_bitop3_b32 v4, v4, v3, 32 bitop3:0x6c
	v_ashrrev_i32_e32 v3, 31, v4
	v_lshrrev_b32_e32 v3, 26, v3
	v_add_u32_e32 v5, v4, v3
	v_lshlrev_b32_e32 v6, 3, v2
	v_ashrrev_i32_e32 v3, 6, v5
	v_and_b32_e32 v6, -16, v6
	v_add_u32_e32 v6, v3, v6
	v_and_b32_e32 v7, 3, v3
	s_mov_b32 s14, 0xfffe0
	v_lshrrev_b32_e32 v9, 2, v6
	v_lshlrev_b32_e32 v10, 1, v6
	v_and_b32_e32 v5, 0xc0, v5
	v_and_or_b32 v7, v6, s14, v7
	v_and_b32_e32 v9, 4, v9
	v_and_b32_e32 v10, 24, v10
	v_sub_u32_e32 v4, v4, v5
	v_or3_b32 v7, v7, v9, v10
	v_lshlrev_b32_e32 v9, 5, v2
	v_ashrrev_i16_sdwa v4, v225, sext(v4) dst_sel:DWORD dst_unused:UNUSED_PAD src0_sel:DWORD src1_sel:BYTE_0
	v_and_b32_e32 v9, 32, v9
	v_bfe_i32 v4, v4, 0, 16
	v_add_lshl_u32 v5, v9, v4, 1
	v_lshl_add_u32 v130, v7, 12, v5
	v_lshl_add_u32 v132, v6, 12, v5
	v_bfe_i32 v5, v8, 27, 1
	v_lshrrev_b32_e32 v5, 22, v5
	v_add_u32_e32 v5, v0, v5
	v_and_b32_e32 v5, 0xfffffc00, v5
	v_sub_u32_e32 v0, v0, v5
	v_lshrrev_b32_e32 v5, 4, v0
	v_ashrrev_i32_e32 v6, 31, v8
	v_bitop3_b32 v0, v5, v0, 32 bitop3:0x6c
	v_lshrrev_b32_e32 v6, 26, v6
	v_ashrrev_i32_e32 v5, 31, v0
	v_add_u32_e32 v6, v8, v6
	v_lshrrev_b32_e32 v5, 26, v5
	v_ashrrev_i32_e32 v6, 6, v6
	v_add_u32_e32 v7, v0, v5
	v_lshlrev_b32_e32 v9, 3, v6
	v_ashrrev_i32_e32 v5, 6, v7
	v_and_b32_e32 v9, -16, v9
	v_add_u32_e32 v9, v5, v9
	v_and_b32_e32 v10, 3, v5
	v_lshrrev_b32_e32 v11, 2, v9
	v_lshlrev_b32_e32 v12, 1, v9
	v_and_b32_e32 v7, 0xc0, v7
	v_and_or_b32 v10, v9, s14, v10
	v_and_b32_e32 v11, 4, v11
	v_and_b32_e32 v12, 24, v12
	v_sub_u32_e32 v0, v0, v7
	s_ashr_i32 s1, s0, 6
	v_or3_b32 v10, v10, v11, v12
	v_lshlrev_b32_e32 v11, 5, v6
	v_ashrrev_i16_sdwa v0, v225, sext(v0) dst_sel:DWORD dst_unused:UNUSED_PAD src0_sel:DWORD src1_sel:BYTE_0
	s_lshl_b32 s38, s1, 10
	v_and_b32_e32 v11, 32, v11
	v_bfe_i32 v7, v0, 0, 16
	v_add_lshl_u32 v11, v11, v7, 1
	s_add_i32 s39, s38, 0
	v_lshl_add_u32 v0, v10, 12, v11
	s_add_i32 m0, s39, 0x10000
	v_readlane_b32 s14, v249, 53
	global_load_lds_dwordx4 v0, s[6:7]
	s_add_i32 m0, s39, 0x12000
	v_lshl_add_u32 v134, v9, 12, v11
	global_load_lds_dwordx4 v130, s[6:7]
	s_add_i32 m0, s39, 0x14000
	v_readlane_b32 s15, v249, 54
	global_load_lds_dwordx4 v0, s[8:9]
	s_add_i32 m0, s39, 0x16000
	s_add_i32 s58, s39, 0x2000
	global_load_lds_dwordx4 v130, s[8:9]
	s_mov_b32 m0, s39
	s_add_i32 s60, s39, 0x4000
	global_load_lds_dwordx4 v134, s[14:15]
	s_mov_b32 m0, s58
	s_add_i32 s61, s39, 0x6000
	global_load_lds_dwordx4 v132, s[14:15]
	v_readlane_b32 s14, v249, 55
	s_mov_b32 m0, s60
	v_readlane_b32 s15, v249, 56
	s_ashr_i32 s24, s0, 8
	s_cmp_eq_u32 s24, 1
	s_nop 2
	global_load_lds_dwordx4 v134, s[14:15]
	s_mov_b32 m0, s61
	s_nop 0
	global_load_lds_dwordx4 v132, s[14:15]
	s_cselect_b64 s[14:15], -1, 0
	s_cmp_lg_u32 s24, 1
	s_cbranch_scc1 .LBB0_1487
	s_barrier

; #define LAS __attribute__((address_space(3)))
; __global__ void __launch_bounds__(512, 2) mega(Args a) {
;     extern __shared__ __attribute__((aligned(16))) unsigned char lds_raw[];
;     cg::grid_group grid = cg::this_grid();
;     LAS unsigned char* lds = (LAS unsigned char*)lds_raw;
;     const int tid = threadIdx.x, lane = tid & 63, wave = __builtin_amdgcn_readfirstlane(tid >> 6);
;     const int G = gridDim.x, gw = blockIdx.x * 8 + wave, NGW = G * 8;
;     LAS unsigned char* wl = lds + wave * WAVE_LDS;
	.amdhsa_kernel _ZN2mk4megaENS_4ArgsE
		.amdhsa_group_segment_fixed_size 0
		.amdhsa_private_segment_fixed_size 0
		.amdhsa_kernarg_size 392
		.amdhsa_user_sgpr_count 2
		.amdhsa_user_sgpr_dispatch_ptr 0
		.amdhsa_user_sgpr_queue_ptr 0
		.amdhsa_user_sgpr_kernarg_segment_ptr 1
		.amdhsa_user_sgpr_dispatch_id 0
		.amdhsa_user_sgpr_kernarg_preload_length 0
		.amdhsa_user_sgpr_kernarg_preload_offset 0
		.amdhsa_user_sgpr_private_segment_size 0
		.amdhsa_uses_dynamic_stack 0
		.amdhsa_enable_private_segment 0
		.amdhsa_system_sgpr_workgroup_id_x 1
		.amdhsa_system_sgpr_workgroup_id_y 0
		.amdhsa_system_sgpr_workgroup_id_z 0
		.amdhsa_system_sgpr_workgroup_info 0
		.amdhsa_system_vgpr_workitem_id 2
		.amdhsa_next_free_vgpr 251
		.amdhsa_next_free_sgpr 99
		.amdhsa_accum_offset 252
		.amdhsa_reserve_vcc 1
		.amdhsa_float_round_mode_32 0
		.amdhsa_float_round_mode_16_64 0
		.amdhsa_float_denorm_mode_32 3
		.amdhsa_float_denorm_mode_16_64 3
		.amdhsa_dx10_clamp 1
		.amdhsa_ieee_mode 1
		.amdhsa_fp16_overflow 0
		.amdhsa_tg_split 0
		.amdhsa_exception_fp_ieee_invalid_op 0
		.amdhsa_exception_fp_denorm_src 0
		.amdhsa_exception_fp_ieee_div_zero 0
		.amdhsa_exception_fp_ieee_overflow 0
		.amdhsa_exception_fp_ieee_underflow 0
		.amdhsa_exception_fp_ieee_inexact 0
		.amdhsa_exception_int_div_zero 0
	.end_amdhsa_kernel

; __global__ void __launch_bounds__(512, 2) mega(Args a) {
amdhsa.kernels:
  - .agpr_count:     0
    .args:
      - .offset:         0
        .size:           136
        .value_kind:     by_value
      - .offset:         136
        .size:           4
        .value_kind:     hidden_block_count_x
      - .offset:         140
        .size:           4
        .value_kind:     hidden_block_count_y
      - .offset:         144
        .size:           4
        .value_kind:     hidden_block_count_z
      - .offset:         148
        .size:           2
        .value_kind:     hidden_group_size_x
      - .offset:         150
        .size:           2
        .value_kind:     hidden_group_size_y
      - .offset:         152
        .size:           2
        .value_kind:     hidden_group_size_z
      - .offset:         154
        .size:           2
        .value_kind:     hidden_remainder_x
      - .offset:         156
        .size:           2
        .value_kind:     hidden_remainder_y
      - .offset:         158
        .size:           2
        .value_kind:     hidden_remainder_z
      - .offset:         176
        .size:           8
        .value_kind:     hidden_global_offset_x
      - .offset:         184
        .size:           8
        .value_kind:     hidden_global_offset_y
      - .offset:         192
        .size:           8
        .value_kind:     hidden_global_offset_z
      - .offset:         200
        .size:           2
        .value_kind:     hidden_grid_dims
      - .offset:         224
        .size:           8
        .value_kind:     hidden_multigrid_sync_arg
      - .offset:         256
        .size:           4
        .value_kind:     hidden_dynamic_lds_size
    .group_segment_fixed_size: 0
    .kernarg_segment_align: 8
    .kernarg_segment_size: 392
    .language:       OpenCL C
    .language_version:
      - 2
      - 0
    .max_flat_workgroup_size: 512
    .name:           _ZN2mk4megaENS_4ArgsE
    .private_segment_fixed_size: 0
    .sgpr_count:     105
    .sgpr_spill_count: 197
    .symbol:         _ZN2mk4megaENS_4ArgsE.kd
    .uniform_work_group_size: 1
    .uses_dynamic_stack: false
    .vgpr_count:     251
    .vgpr_spill_count: 0
    .wavefront_size: 64
